# epilogues no longer aligned between the two wave halves (leading half keeps its one-barrier lead through the epilogue)
# baseline (speedup 1.0000x reference)
.Lzskip_0:
	s_and_b64 vcc, exec, s[76:77]
	s_cbranch_vccz .LBB0_123
.LBB0_123:
	v_lshl_add_u32 v164, s86, 8, v174
	v_or_b32_e32 v160, 16, v164
	v_or_b32_e32 v158, 32, v164
	v_or_b32_e32 v156, 48, v164
	s_mov_b64 s[52:53], -1
	s_cmp_gt_u32 s55, 13
	v_ashrrev_i32_e32 v165, 31, v164
	v_ashrrev_i32_e32 v161, 31, v160
	v_ashrrev_i32_e32 v159, 31, v158
	v_ashrrev_i32_e32 v157, 31, v156
	v_add_u32_e32 v168, 0x80, v164
	s_cbranch_scc0 .LBB0_125
	v_lshlrev_b64 v[128:129], 6, v[164:165]
	v_lshl_add_u64 v[128:129], v[146:147], 0, v[128:129]
	global_load_dwordx4 v[184:187], v[128:129], off
	v_lshlrev_b64 v[130:131], 6, v[160:161]
	v_lshl_add_u64 v[130:131], v[146:147], 0, v[130:131]
	global_load_dwordx4 v[188:191], v[130:131], off
	v_lshlrev_b64 v[130:131], 6, v[158:159]
	v_lshl_add_u64 v[130:131], v[146:147], 0, v[130:131]
	global_load_dwordx4 v[192:195], v[130:131], off
	v_lshlrev_b64 v[130:131], 6, v[156:157]
	v_lshl_add_u64 v[130:131], v[146:147], 0, v[130:131]
	global_load_dwordx4 v[196:199], v[130:131], off
	v_add_u32_e32 v154, 0x80, v164
	v_ashrrev_i32_e32 v155, 31, v154
	v_lshlrev_b64 v[130:131], 6, v[154:155]
	v_lshl_add_u64 v[130:131], v[146:147], 0, v[130:131]
	global_load_dwordx4 v[200:203], v[130:131], off
	s_movk_i32 s52, 0x2000
	v_add_co_u32_e32 v128, vcc, s52, v128
	v_xor_b32_e32 v162, 16, v172
	s_nop 0
	v_addc_co_u32_e32 v129, vcc, 0, v129, vcc
	v_cmp_lt_i32_e32 vcc, v162, v173
	global_load_dwordx4 v[204:207], v[128:129], off offset:1024
	global_load_dwordx4 v[132:135], v[128:129], off offset:2048
	s_nop 0
	global_load_dwordx4 v[128:131], v[128:129], off offset:3072
	v_cndmask_b32_e32 v162, v172, v162, vcc
	v_lshlrev_b32_e32 v169, 2, v162
	v_xor_b32_e32 v162, 32, v172
	v_cmp_lt_i32_e32 vcc, v162, v173
	s_mov_b64 s[52:53], 0
	s_waitcnt vmcnt(0)
	v_mov_b32_e32 v163, v186
	v_cndmask_b32_e32 v162, v172, v162, vcc
	v_lshlrev_b32_e32 v182, 2, v162
	v_mov_b32_e32 v162, v185
	v_mov_b32_e32 v185, v187
	v_pk_add_f32 v[162:163], v[162:163], v[184:185]
	v_mov_b32_e32 v184, v205
	v_add_f32_e32 v162, v162, v163
	ds_bpermute_b32 v163, v169, v162
	v_mov_b32_e32 v185, v206
	v_mov_b32_e32 v205, v207
	v_pk_add_f32 v[184:185], v[184:185], v[204:205]
	s_waitcnt lgkmcnt(0)
	v_add_f32_e32 v162, v162, v163
	ds_bpermute_b32 v163, v182, v162
	s_waitcnt lgkmcnt(0)
	v_add_f32_e32 v162, v162, v163
	v_fmamk_f32 v162, v162, 0x3a800000, v181
	v_rsq_f32_e32 v170, v162
	v_mov_b32_e32 v162, v189
	v_mov_b32_e32 v163, v190
	v_mov_b32_e32 v189, v191
	v_pk_add_f32 v[162:163], v[162:163], v[188:189]
	s_nop 0
	v_add_f32_e32 v162, v162, v163
	ds_bpermute_b32 v163, v169, v162
	s_waitcnt lgkmcnt(0)
	v_add_f32_e32 v162, v162, v163
	ds_bpermute_b32 v163, v182, v162
	s_waitcnt lgkmcnt(0)
	v_add_f32_e32 v162, v162, v163
	v_fmamk_f32 v162, v162, 0x3a800000, v181
	v_rsq_f32_e32 v171, v162
	v_mov_b32_e32 v162, v193
	v_mov_b32_e32 v163, v194
	v_mov_b32_e32 v193, v195
	v_pk_add_f32 v[162:163], v[162:163], v[192:193]
	s_nop 0
	v_add_f32_e32 v162, v162, v163
	ds_bpermute_b32 v163, v169, v162
	s_waitcnt lgkmcnt(0)
	v_add_f32_e32 v162, v162, v163
	ds_bpermute_b32 v163, v182, v162
	s_waitcnt lgkmcnt(0)
	v_add_f32_e32 v162, v162, v163
	v_fmamk_f32 v162, v162, 0x3a800000, v181
	v_rsq_f32_e32 v166, v162
	v_mov_b32_e32 v162, v197
	v_mov_b32_e32 v163, v198
	v_mov_b32_e32 v197, v199
	v_pk_add_f32 v[162:163], v[162:163], v[196:197]
	s_nop 0
	v_add_f32_e32 v162, v162, v163
	ds_bpermute_b32 v163, v169, v162
	s_waitcnt lgkmcnt(0)
	v_add_f32_e32 v162, v162, v163
	ds_bpermute_b32 v163, v182, v162
	s_waitcnt lgkmcnt(0)
	v_add_f32_e32 v162, v162, v163
	v_fmamk_f32 v162, v162, 0x3a800000, v181
	v_rsq_f32_e32 v167, v162
	v_mov_b32_e32 v162, v201
	v_mov_b32_e32 v163, v202
	v_mov_b32_e32 v201, v203
	v_pk_add_f32 v[162:163], v[162:163], v[200:201]
	s_nop 0
	v_add_f32_e32 v162, v162, v163
	ds_bpermute_b32 v163, v169, v162
	s_waitcnt lgkmcnt(0)
	v_add_f32_e32 v162, v162, v163
	ds_bpermute_b32 v163, v182, v162
	s_waitcnt lgkmcnt(0)
	v_add_f32_e32 v162, v162, v163
	v_add_f32_e32 v163, v184, v185
	v_mov_b32_e32 v184, v133
	v_mov_b32_e32 v185, v134
	v_mov_b32_e32 v133, v135
	v_mov_b32_e32 v134, v129
	v_mov_b32_e32 v135, v130
	v_mov_b32_e32 v129, v131
	v_pk_add_f32 v[132:133], v[184:185], v[132:133]
	v_pk_add_f32 v[128:129], v[134:135], v[128:129]
	v_add_f32_e32 v132, v132, v133
	v_add_f32_e32 v128, v128, v129
	ds_bpermute_b32 v183, v169, v163
	ds_bpermute_b32 v133, v169, v132
	ds_bpermute_b32 v129, v169, v128
	v_fmamk_f32 v162, v162, 0x3a800000, v181
	v_rsq_f32_e32 v162, v162
	s_waitcnt lgkmcnt(2)
	v_add_f32_e32 v163, v163, v183
	s_waitcnt lgkmcnt(1)
	v_add_f32_e32 v132, v132, v133
	s_waitcnt lgkmcnt(0)
	v_add_f32_e32 v128, v128, v129
	ds_bpermute_b32 v183, v182, v163
	ds_bpermute_b32 v133, v182, v132
	ds_bpermute_b32 v129, v182, v128
	s_waitcnt lgkmcnt(2)
	v_add_f32_e32 v163, v163, v183
	s_waitcnt lgkmcnt(1)
	v_add_f32_e32 v132, v132, v133
	s_waitcnt lgkmcnt(0)
	v_add_f32_e32 v128, v128, v129
	v_fmamk_f32 v163, v163, 0x3a800000, v181
	v_fmamk_f32 v132, v132, 0x3a800000, v181
	v_fmamk_f32 v128, v128, 0x3a800000, v181
	v_rsq_f32_e32 v163, v163
	v_rsq_f32_e32 v132, v132
	v_rsq_f32_e32 v133, v128
	v_mov_b64_e32 v[128:129], v[154:155]

.LBB0_127:
	s_waitcnt lgkmcnt(0)
	v_mul_f32_e32 v130, 0xbfb8aa3b, v170
	v_mul_f32_e32 v131, v170, v170
	v_pk_mul_f32 v[168:169], v[126:127], v[130:131] op_sel_hi:[1,0]
	v_rcp_f32_e32 v134, v131
	v_pk_mul_f32 v[182:183], v[124:125], v[130:131] op_sel_hi:[1,0]
	v_exp_f32_e32 v168, v168
	v_exp_f32_e32 v169, v169
	v_pk_mul_f32 v[122:123], v[126:127], v[122:123]
	v_pk_mul_f32 v[126:127], v[116:117], v[130:131] op_sel_hi:[1,0]
	v_exp_f32_e32 v182, v182
	v_exp_f32_e32 v183, v183
	v_exp_f32_e32 v126, v126
	v_exp_f32_e32 v127, v127
	v_pk_mul_f32 v[120:121], v[124:125], v[120:121]
	v_pk_mul_f32 v[124:125], v[118:119], v[130:131] op_sel_hi:[1,0]
	v_pk_fma_f32 v[168:169], v[168:169], v[134:135], v[134:135] op_sel_hi:[1,0,0]
	v_exp_f32_e32 v124, v124
	v_exp_f32_e32 v125, v125
	v_pk_fma_f32 v[182:183], v[182:183], v[134:135], v[134:135] op_sel_hi:[1,0,0]
	v_rcp_f32_e32 v168, v168
	v_rcp_f32_e32 v169, v169
	v_pk_fma_f32 v[126:127], v[126:127], v[134:135], v[134:135] op_sel_hi:[1,0,0]
	v_rcp_f32_e32 v182, v182
	v_rcp_f32_e32 v183, v183
	v_rcp_f32_e32 v126, v126
	v_rcp_f32_e32 v127, v127
	v_pk_fma_f32 v[124:125], v[124:125], v[134:135], v[134:135] op_sel_hi:[1,0,0]
	v_pk_mul_f32 v[122:123], v[122:123], v[168:169]
	v_rcp_f32_e32 v124, v124
	v_rcp_f32_e32 v125, v125
	v_pk_mul_f32 v[112:113], v[116:117], v[112:113]
	v_pk_mul_f32 v[120:121], v[120:121], v[182:183]
	v_pk_mul_f32 v[112:113], v[112:113], v[126:127]
	v_cvt_pk_bf16_f32 v116, v120, v121
	v_cvt_pk_bf16_f32 v117, v122, v123
	v_mul_f32_e32 v122, 0xbfb8aa3b, v171
	v_mul_f32_e32 v123, v171, v171
	v_pk_mul_f32 v[114:115], v[118:119], v[114:115]
	v_cvt_pk_bf16_f32 v118, v112, v113
	v_mov_b64_e32 v[112:113], s[64:65]
	v_pk_mul_f32 v[126:127], v[110:111], v[122:123] op_sel_hi:[1,0]
	v_pk_mul_f32 v[130:131], v[108:109], v[122:123] op_sel_hi:[1,0]
	v_pk_mul_f32 v[106:107], v[110:111], v[106:107]
	v_pk_mul_f32 v[104:105], v[108:109], v[104:105]
	v_pk_mul_f32 v[108:109], v[102:103], v[122:123] op_sel_hi:[1,0]
	v_pk_mul_f32 v[110:111], v[100:101], v[122:123] op_sel_hi:[1,0]
	v_pk_mul_f32 v[114:115], v[114:115], v[124:125]
	v_mad_u64_u32 v[120:121], s[52:53], v164, s27, v[112:113]
	v_rcp_f32_e32 v124, v123
	v_exp_f32_e32 v110, v110
	v_exp_f32_e32 v108, v108
	v_exp_f32_e32 v109, v109
	v_exp_f32_e32 v111, v111
	v_lshl_or_b32 v184, s54, 7, v177
	v_cvt_pk_bf16_f32 v119, v114, v115
	v_exp_f32_e32 v130, v130
	v_exp_f32_e32 v126, v126
	v_exp_f32_e32 v127, v127
	v_exp_f32_e32 v131, v131
	v_ashrrev_i32_e32 v185, 31, v184
	v_lshlrev_b64 v[114:115], 1, v[184:185]
	v_lshl_add_u64 v[120:121], v[120:121], 0, v[114:115]
	v_pk_fma_f32 v[108:109], v[108:109], v[124:125], v[124:125] op_sel_hi:[1,0,0]
	v_pk_fma_f32 v[110:111], v[110:111], v[124:125], v[124:125] op_sel_hi:[1,0,0]
	global_store_dwordx4 v[120:121], v[116:119], off
	v_rcp_f32_e32 v110, v110
	v_rcp_f32_e32 v108, v108
	v_pk_fma_f32 v[116:117], v[126:127], v[124:125], v[124:125] op_sel_hi:[1,0,0]
	v_pk_fma_f32 v[118:119], v[130:131], v[124:125], v[124:125] op_sel_hi:[1,0,0]
	v_rcp_f32_e32 v109, v109
	v_rcp_f32_e32 v111, v111
	v_rcp_f32_e32 v118, v118
	v_rcp_f32_e32 v119, v119
	v_rcp_f32_e32 v116, v116
	v_rcp_f32_e32 v117, v117
	v_pk_mul_f32 v[98:99], v[102:103], v[98:99]
	v_pk_mul_f32 v[96:97], v[100:101], v[96:97]
	v_pk_mul_f32 v[100:101], v[98:99], v[108:109]
	v_pk_mul_f32 v[98:99], v[96:97], v[110:111]
	v_pk_mul_f32 v[106:107], v[106:107], v[116:117]
	v_pk_mul_f32 v[104:105], v[104:105], v[118:119]
	v_pk_mul_f32 v[90:91], v[94:95], v[90:91]
	v_cvt_pk_bf16_f32 v96, v104, v105
	v_cvt_pk_bf16_f32 v97, v106, v107
	v_cvt_pk_bf16_f32 v98, v98, v99
	v_cvt_pk_bf16_f32 v99, v100, v101
	v_mad_u64_u32 v[100:101], s[52:53], v160, s27, v[112:113]
	v_mul_f32_e32 v102, 0xbfb8aa3b, v166
	v_mul_f32_e32 v103, v166, v166
	v_pk_mul_f32 v[106:107], v[94:95], v[102:103] op_sel_hi:[1,0]
	v_pk_mul_f32 v[108:109], v[92:93], v[102:103] op_sel_hi:[1,0]
	v_pk_mul_f32 v[88:89], v[92:93], v[88:89]
	v_pk_mul_f32 v[92:93], v[86:87], v[102:103] op_sel_hi:[1,0]
	v_pk_mul_f32 v[94:95], v[84:85], v[102:103] op_sel_hi:[1,0]
	v_rcp_f32_e32 v104, v103
	v_exp_f32_e32 v94, v94
	v_exp_f32_e32 v92, v92
	v_exp_f32_e32 v93, v93
	v_exp_f32_e32 v95, v95
	v_exp_f32_e32 v108, v108
	v_exp_f32_e32 v106, v106
	v_exp_f32_e32 v107, v107
	v_exp_f32_e32 v109, v109
	v_lshl_add_u64 v[100:101], v[100:101], 0, v[114:115]
	v_pk_fma_f32 v[92:93], v[92:93], v[104:105], v[104:105] op_sel_hi:[1,0,0]
	v_pk_fma_f32 v[94:95], v[94:95], v[104:105], v[104:105] op_sel_hi:[1,0,0]
	global_store_dwordx4 v[100:101], v[96:99], off
	v_rcp_f32_e32 v94, v94
	v_rcp_f32_e32 v92, v92
	v_pk_fma_f32 v[96:97], v[106:107], v[104:105], v[104:105] op_sel_hi:[1,0,0]
	v_pk_fma_f32 v[98:99], v[108:109], v[104:105], v[104:105] op_sel_hi:[1,0,0]
	v_rcp_f32_e32 v93, v93
	v_rcp_f32_e32 v95, v95
	v_rcp_f32_e32 v98, v98
	v_rcp_f32_e32 v99, v99
	v_rcp_f32_e32 v96, v96
	v_rcp_f32_e32 v97, v97
	v_pk_mul_f32 v[82:83], v[86:87], v[82:83]
	v_pk_mul_f32 v[80:81], v[84:85], v[80:81]
	v_pk_mul_f32 v[84:85], v[82:83], v[92:93]
	v_pk_mul_f32 v[82:83], v[80:81], v[94:95]
	v_pk_mul_f32 v[90:91], v[90:91], v[96:97]
	v_pk_mul_f32 v[88:89], v[88:89], v[98:99]
	v_pk_mul_f32 v[74:75], v[78:79], v[74:75]
	v_cvt_pk_bf16_f32 v80, v88, v89
	v_cvt_pk_bf16_f32 v81, v90, v91
	v_cvt_pk_bf16_f32 v82, v82, v83
	v_cvt_pk_bf16_f32 v83, v84, v85
	v_mad_u64_u32 v[84:85], s[52:53], v158, s27, v[112:113]
	v_mul_f32_e32 v86, 0xbfb8aa3b, v167
	v_mul_f32_e32 v87, v167, v167
	v_pk_mul_f32 v[90:91], v[78:79], v[86:87] op_sel_hi:[1,0]
	v_pk_mul_f32 v[92:93], v[76:77], v[86:87] op_sel_hi:[1,0]
	v_pk_mul_f32 v[72:73], v[76:77], v[72:73]
	v_pk_mul_f32 v[76:77], v[70:71], v[86:87] op_sel_hi:[1,0]
	v_pk_mul_f32 v[78:79], v[68:69], v[86:87] op_sel_hi:[1,0]
	v_rcp_f32_e32 v88, v87
	v_exp_f32_e32 v78, v78
	v_exp_f32_e32 v76, v76
	v_exp_f32_e32 v77, v77
	v_exp_f32_e32 v79, v79
	v_exp_f32_e32 v92, v92
	v_exp_f32_e32 v90, v90
	v_exp_f32_e32 v91, v91
	v_exp_f32_e32 v93, v93
	v_lshl_add_u64 v[84:85], v[84:85], 0, v[114:115]
	v_pk_fma_f32 v[76:77], v[76:77], v[88:89], v[88:89] op_sel_hi:[1,0,0]
	v_pk_fma_f32 v[78:79], v[78:79], v[88:89], v[88:89] op_sel_hi:[1,0,0]
	global_store_dwordx4 v[84:85], v[80:83], off
	v_rcp_f32_e32 v78, v78
	v_rcp_f32_e32 v76, v76
	v_pk_fma_f32 v[80:81], v[90:91], v[88:89], v[88:89] op_sel_hi:[1,0,0]
	v_pk_fma_f32 v[82:83], v[92:93], v[88:89], v[88:89] op_sel_hi:[1,0,0]
	v_rcp_f32_e32 v77, v77
	v_rcp_f32_e32 v79, v79
	v_rcp_f32_e32 v82, v82
	v_rcp_f32_e32 v83, v83
	v_rcp_f32_e32 v80, v80
	v_rcp_f32_e32 v81, v81
	v_pk_mul_f32 v[66:67], v[70:71], v[66:67]
	v_pk_mul_f32 v[64:65], v[68:69], v[64:65]
	v_pk_mul_f32 v[68:69], v[66:67], v[76:77]
	v_pk_mul_f32 v[66:67], v[64:65], v[78:79]
	v_pk_mul_f32 v[74:75], v[74:75], v[80:81]
	v_pk_mul_f32 v[72:73], v[72:73], v[82:83]
	v_pk_mul_f32 v[58:59], v[62:63], v[58:59]
	v_cvt_pk_bf16_f32 v64, v72, v73
	v_cvt_pk_bf16_f32 v65, v74, v75
	v_cvt_pk_bf16_f32 v66, v66, v67
	v_cvt_pk_bf16_f32 v67, v68, v69
	v_mad_u64_u32 v[68:69], s[52:53], v156, s27, v[112:113]
	v_mul_f32_e32 v70, 0xbfb8aa3b, v162
	v_mul_f32_e32 v71, v162, v162
	v_pk_mul_f32 v[74:75], v[62:63], v[70:71] op_sel_hi:[1,0]
	v_pk_mul_f32 v[76:77], v[60:61], v[70:71] op_sel_hi:[1,0]
	v_pk_mul_f32 v[56:57], v[60:61], v[56:57]
	v_pk_mul_f32 v[60:61], v[54:55], v[70:71] op_sel_hi:[1,0]
	v_pk_mul_f32 v[62:63], v[52:53], v[70:71] op_sel_hi:[1,0]
	v_rcp_f32_e32 v72, v71
	v_exp_f32_e32 v62, v62
	v_exp_f32_e32 v60, v60
	v_exp_f32_e32 v61, v61
	v_exp_f32_e32 v63, v63
	v_exp_f32_e32 v76, v76
	v_exp_f32_e32 v74, v74
	v_exp_f32_e32 v75, v75
	v_exp_f32_e32 v77, v77
	v_lshl_add_u64 v[68:69], v[68:69], 0, v[114:115]
	v_pk_fma_f32 v[60:61], v[60:61], v[72:73], v[72:73] op_sel_hi:[1,0,0]
	v_pk_fma_f32 v[62:63], v[62:63], v[72:73], v[72:73] op_sel_hi:[1,0,0]
	global_store_dwordx4 v[68:69], v[64:67], off
	v_rcp_f32_e32 v62, v62
	v_rcp_f32_e32 v60, v60
	v_pk_fma_f32 v[64:65], v[74:75], v[72:73], v[72:73] op_sel_hi:[1,0,0]
	v_pk_fma_f32 v[66:67], v[76:77], v[72:73], v[72:73] op_sel_hi:[1,0,0]
	v_rcp_f32_e32 v61, v61
	v_rcp_f32_e32 v63, v63
	v_rcp_f32_e32 v66, v66
	v_rcp_f32_e32 v67, v67
	v_rcp_f32_e32 v64, v64
	v_rcp_f32_e32 v65, v65
	v_pk_mul_f32 v[50:51], v[54:55], v[50:51]
	v_pk_mul_f32 v[48:49], v[52:53], v[48:49]
	v_pk_mul_f32 v[52:53], v[50:51], v[60:61]
	v_pk_mul_f32 v[50:51], v[48:49], v[62:63]
	v_pk_mul_f32 v[58:59], v[58:59], v[64:65]
	v_pk_mul_f32 v[56:57], v[56:57], v[66:67]
	v_pk_mul_f32 v[42:43], v[46:47], v[42:43]
	v_cvt_pk_bf16_f32 v48, v56, v57
	v_cvt_pk_bf16_f32 v49, v58, v59
	v_cvt_pk_bf16_f32 v50, v50, v51
	v_cvt_pk_bf16_f32 v51, v52, v53
	v_mad_u64_u32 v[52:53], s[52:53], v128, s27, v[112:113]
	v_mov_b32_e32 v54, v53
	v_mad_u64_u32 v[54:55], s[52:53], v129, s27, v[54:55]
	v_mov_b32_e32 v53, v54
	v_mul_f32_e32 v54, 0xbfb8aa3b, v163
	v_mul_f32_e32 v55, v163, v163
	v_pk_mul_f32 v[58:59], v[46:47], v[54:55] op_sel_hi:[1,0]
	v_pk_mul_f32 v[60:61], v[44:45], v[54:55] op_sel_hi:[1,0]
	v_pk_mul_f32 v[40:41], v[44:45], v[40:41]
	v_pk_mul_f32 v[44:45], v[38:39], v[54:55] op_sel_hi:[1,0]
	v_pk_mul_f32 v[46:47], v[36:37], v[54:55] op_sel_hi:[1,0]
	v_rcp_f32_e32 v56, v55
	v_exp_f32_e32 v46, v46
	v_exp_f32_e32 v44, v44
	v_exp_f32_e32 v45, v45
	v_exp_f32_e32 v47, v47
	v_exp_f32_e32 v60, v60
	v_exp_f32_e32 v58, v58
	v_exp_f32_e32 v59, v59
	v_exp_f32_e32 v61, v61
	v_lshl_add_u64 v[52:53], v[52:53], 0, v[114:115]
	v_pk_fma_f32 v[44:45], v[44:45], v[56:57], v[56:57] op_sel_hi:[1,0,0]
	v_pk_fma_f32 v[46:47], v[46:47], v[56:57], v[56:57] op_sel_hi:[1,0,0]
	global_store_dwordx4 v[52:53], v[48:51], off
	v_rcp_f32_e32 v46, v46
	v_rcp_f32_e32 v44, v44
	v_pk_fma_f32 v[48:49], v[58:59], v[56:57], v[56:57] op_sel_hi:[1,0,0]
	v_pk_fma_f32 v[50:51], v[60:61], v[56:57], v[56:57] op_sel_hi:[1,0,0]
	v_rcp_f32_e32 v45, v45
	v_rcp_f32_e32 v47, v47
	v_rcp_f32_e32 v50, v50
	v_rcp_f32_e32 v51, v51
	v_rcp_f32_e32 v48, v48
	v_rcp_f32_e32 v49, v49
	v_pk_mul_f32 v[34:35], v[38:39], v[34:35]
	v_pk_mul_f32 v[32:33], v[36:37], v[32:33]
	v_pk_mul_f32 v[36:37], v[34:35], v[44:45]
	v_pk_mul_f32 v[34:35], v[32:33], v[46:47]
	v_add_u32_e32 v38, 16, v154
	v_pk_mul_f32 v[42:43], v[42:43], v[48:49]
	v_pk_mul_f32 v[40:41], v[40:41], v[50:51]
	v_mul_f32_e32 v39, v132, v132
	v_cvt_pk_bf16_f32 v32, v40, v41
	v_cvt_pk_bf16_f32 v33, v42, v43
	v_cvt_pk_bf16_f32 v34, v34, v35
	v_cvt_pk_bf16_f32 v35, v36, v37
	v_mad_i64_i32 v[36:37], s[52:53], v38, s27, v[112:113]
	v_mul_f32_e32 v38, 0xbfb8aa3b, v132
	v_pk_mul_f32 v[42:43], v[30:31], v[38:39] op_sel_hi:[1,0]
	v_pk_mul_f32 v[44:45], v[28:29], v[38:39] op_sel_hi:[1,0]
	v_pk_mul_f32 v[26:27], v[30:31], v[26:27]
	v_pk_mul_f32 v[24:25], v[28:29], v[24:25]
	v_pk_mul_f32 v[28:29], v[22:23], v[38:39] op_sel_hi:[1,0]
	v_pk_mul_f32 v[30:31], v[20:21], v[38:39] op_sel_hi:[1,0]
	v_rcp_f32_e32 v40, v39
	v_exp_f32_e32 v30, v30
	v_exp_f32_e32 v28, v28
	v_exp_f32_e32 v29, v29
	v_exp_f32_e32 v31, v31
	v_exp_f32_e32 v44, v44
	v_exp_f32_e32 v42, v42
	v_exp_f32_e32 v43, v43
	v_exp_f32_e32 v45, v45
	v_lshl_add_u64 v[36:37], v[36:37], 0, v[114:115]
	v_pk_fma_f32 v[28:29], v[28:29], v[40:41], v[40:41] op_sel_hi:[1,0,0]
	v_pk_fma_f32 v[30:31], v[30:31], v[40:41], v[40:41] op_sel_hi:[1,0,0]
	global_store_dwordx4 v[36:37], v[32:35], off
	v_rcp_f32_e32 v30, v30
	v_rcp_f32_e32 v28, v28
	v_pk_fma_f32 v[32:33], v[42:43], v[40:41], v[40:41] op_sel_hi:[1,0,0]
	v_pk_fma_f32 v[34:35], v[44:45], v[40:41], v[40:41] op_sel_hi:[1,0,0]
	v_rcp_f32_e32 v29, v29
	v_rcp_f32_e32 v31, v31
	v_rcp_f32_e32 v34, v34
	v_rcp_f32_e32 v35, v35
	v_rcp_f32_e32 v32, v32
	v_rcp_f32_e32 v33, v33
	v_pk_mul_f32 v[18:19], v[22:23], v[18:19]
	v_pk_mul_f32 v[16:17], v[20:21], v[16:17]
	v_pk_mul_f32 v[20:21], v[18:19], v[28:29]
	v_pk_mul_f32 v[18:19], v[16:17], v[30:31]
	v_add_u32_e32 v22, 32, v154
	v_pk_mul_f32 v[26:27], v[26:27], v[32:33]
	v_pk_mul_f32 v[24:25], v[24:25], v[34:35]
	v_mul_f32_e32 v23, v133, v133
	v_cvt_pk_bf16_f32 v16, v24, v25
	v_cvt_pk_bf16_f32 v17, v26, v27
	v_cvt_pk_bf16_f32 v18, v18, v19
	v_cvt_pk_bf16_f32 v19, v20, v21
	v_mad_i64_i32 v[20:21], s[52:53], v22, s27, v[112:113]
	v_mul_f32_e32 v22, 0xbfb8aa3b, v133
	v_pk_mul_f32 v[26:27], v[14:15], v[22:23] op_sel_hi:[1,0]
	v_pk_mul_f32 v[28:29], v[12:13], v[22:23] op_sel_hi:[1,0]
	v_pk_mul_f32 v[10:11], v[14:15], v[10:11]
	v_pk_mul_f32 v[8:9], v[12:13], v[8:9]
	v_pk_mul_f32 v[12:13], v[6:7], v[22:23] op_sel_hi:[1,0]
	v_pk_mul_f32 v[14:15], v[4:5], v[22:23] op_sel_hi:[1,0]
	v_rcp_f32_e32 v24, v23
	v_exp_f32_e32 v14, v14
	v_exp_f32_e32 v12, v12
	v_exp_f32_e32 v13, v13
	v_exp_f32_e32 v15, v15
	v_exp_f32_e32 v28, v28
	v_exp_f32_e32 v26, v26
	v_exp_f32_e32 v27, v27
	v_exp_f32_e32 v29, v29
	v_lshl_add_u64 v[20:21], v[20:21], 0, v[114:115]
	v_pk_fma_f32 v[12:13], v[12:13], v[24:25], v[24:25] op_sel_hi:[1,0,0]
	v_pk_fma_f32 v[14:15], v[14:15], v[24:25], v[24:25] op_sel_hi:[1,0,0]
	global_store_dwordx4 v[20:21], v[16:19], off
	v_rcp_f32_e32 v14, v14
	v_rcp_f32_e32 v12, v12
	v_pk_fma_f32 v[16:17], v[26:27], v[24:25], v[24:25] op_sel_hi:[1,0,0]
	v_pk_fma_f32 v[18:19], v[28:29], v[24:25], v[24:25] op_sel_hi:[1,0,0]
	v_rcp_f32_e32 v13, v13
	v_rcp_f32_e32 v15, v15
	v_rcp_f32_e32 v18, v18
	v_rcp_f32_e32 v19, v19
	v_rcp_f32_e32 v16, v16
	v_rcp_f32_e32 v17, v17
	v_pk_mul_f32 v[2:3], v[6:7], v[2:3]
	v_pk_mul_f32 v[0:1], v[4:5], v[0:1]
	v_pk_mul_f32 v[4:5], v[2:3], v[12:13]
	v_pk_mul_f32 v[2:3], v[0:1], v[14:15]
	v_add_u32_e32 v6, 48, v154
	v_pk_mul_f32 v[10:11], v[10:11], v[16:17]
	v_pk_mul_f32 v[8:9], v[8:9], v[18:19]
	s_andn2_b64 vcc, exec, s[6:7]
	v_cvt_pk_bf16_f32 v0, v8, v9
	v_cvt_pk_bf16_f32 v1, v10, v11
	v_cvt_pk_bf16_f32 v2, v2, v3
	v_cvt_pk_bf16_f32 v3, v4, v5
	v_mad_i64_i32 v[4:5], s[52:53], v6, s27, v[112:113]
	v_lshl_add_u64 v[4:5], v[4:5], 0, v[114:115]
	s_mov_b64 s[6:7], -1
	global_store_dwordx4 v[4:5], v[0:3], off
	s_cbranch_vccnz .LBB0_116
	s_andn2_b64 vcc, exec, s[10:11]
	s_cbranch_vccnz .LBB0_115
	s_branch .LBB0_115
.LBB0_130:
	s_waitcnt vmcnt(0)
	s_and_b64 vcc, exec, s[76:77]
	s_cbranch_vccz .Lua_0
	s_barrier
.Lua_0:
	s_barrier

.Lzskip_1:
	s_and_b64 vcc, exec, s[82:83]
	s_cbranch_vccz .LBB0_275
.LBB0_275:
	v_lshl_or_b32 v204, s52, 8, v244
	v_lshl_add_u32 v234, s53, 8, v242
	v_ashrrev_i32_e32 v205, 31, v204
	v_lshlrev_b64 v[236:237], 1, v[204:205]
	v_ashrrev_i32_e32 v235, 31, v234
	v_lshl_add_u64 v[124:125], s[12:13], 0, v[236:237]
	v_lshlrev_b64 v[238:239], 11, v[234:235]
	v_lshl_add_u64 v[120:121], v[124:125], 0, v[238:239]
	global_load_dwordx4 v[188:191], v[120:121], off
	global_load_dwordx4 v[184:187], v[120:121], off offset:256
	v_or_b32_e32 v230, 16, v234
	v_ashrrev_i32_e32 v231, 31, v230
	v_or_b32_e32 v226, 32, v234
	v_lshlrev_b64 v[232:233], 11, v[230:231]
	v_ashrrev_i32_e32 v227, 31, v226
	v_or_b32_e32 v222, 48, v234
	v_lshl_add_u64 v[120:121], v[124:125], 0, v[232:233]
	v_lshlrev_b64 v[228:229], 11, v[226:227]
	v_ashrrev_i32_e32 v223, 31, v222
	v_add_u32_e32 v218, 0x80, v234
	global_load_dwordx4 v[180:183], v[120:121], off
	global_load_dwordx4 v[176:179], v[120:121], off offset:256
	v_lshl_add_u64 v[120:121], v[124:125], 0, v[228:229]
	v_lshlrev_b64 v[224:225], 11, v[222:223]
	v_ashrrev_i32_e32 v219, 31, v218
	v_add_u32_e32 v214, 0x90, v234
	global_load_dwordx4 v[172:175], v[120:121], off
	global_load_dwordx4 v[168:171], v[120:121], off offset:256
	v_lshl_add_u64 v[120:121], v[124:125], 0, v[224:225]
	v_lshlrev_b64 v[220:221], 11, v[218:219]
	v_ashrrev_i32_e32 v215, 31, v214
	v_add_u32_e32 v210, 0xa0, v234
	v_add_u32_e32 v206, 0xb0, v234
	global_load_dwordx4 v[164:167], v[120:121], off
	global_load_dwordx4 v[160:163], v[120:121], off offset:256
	v_lshl_add_u64 v[120:121], v[124:125], 0, v[220:221]
	v_lshlrev_b64 v[216:217], 11, v[214:215]
	v_ashrrev_i32_e32 v211, 31, v210
	v_ashrrev_i32_e32 v207, 31, v206
	global_load_dwordx4 v[156:159], v[120:121], off
	global_load_dwordx4 v[152:155], v[120:121], off offset:256
	v_lshl_add_u64 v[120:121], v[124:125], 0, v[216:217]
	v_lshlrev_b64 v[212:213], 11, v[210:211]
	v_lshlrev_b64 v[208:209], 11, v[206:207]
	global_load_dwordx4 v[148:151], v[120:121], off
	global_load_dwordx4 v[144:147], v[120:121], off offset:256
	v_lshl_add_u64 v[120:121], v[124:125], 0, v[212:213]
	v_lshl_add_u64 v[124:125], v[124:125], 0, v[208:209]
	global_load_dwordx4 v[128:131], v[120:121], off
	s_nop 0
	global_load_dwordx4 v[120:123], v[120:121], off offset:256
	s_nop 0
	global_load_dwordx4 v[132:135], v[124:125], off
	s_nop 0
	global_load_dwordx4 v[124:127], v[124:125], off offset:256
	v_lshl_add_u64 v[238:239], s[12:13], 0, v[238:239]
	v_lshl_add_u64 v[236:237], v[238:239], 0, v[236:237]
	s_lshl_b32 s86, s52, 2
	s_ashr_i32 s87, s86, 31
	s_waitcnt vmcnt(0)
	v_lshlrev_b32_e32 v250, 16, v188
	v_and_b32_e32 v251, 0xffff0000, v188
	v_lshlrev_b32_e32 v188, 16, v189
	v_and_b32_e32 v189, 0xffff0000, v189
	v_lshlrev_b32_e32 v252, 16, v190
	v_and_b32_e32 v253, 0xffff0000, v190
	v_lshlrev_b32_e32 v190, 16, v191
	v_and_b32_e32 v191, 0xffff0000, v191
	v_pk_fma_f32 v[142:143], v[142:143], 0.5, v[188:189] op_sel_hi:[1,0,1]
	v_pk_fma_f32 v[140:141], v[140:141], 0.5, v[250:251] op_sel_hi:[1,0,1]
	v_pk_fma_f32 v[188:189], v[138:139], 0.5, v[190:191] op_sel_hi:[1,0,1]
	v_pk_fma_f32 v[190:191], v[136:137], 0.5, v[252:253] op_sel_hi:[1,0,1]
	v_cvt_pk_bf16_f32 v136, v140, v141
	v_cvt_pk_bf16_f32 v137, v142, v143
	s_nop 0
	v_cvt_pk_bf16_f32 v138, v190, v191
	v_cvt_pk_bf16_f32 v139, v188, v189
	global_store_dwordx4 v[236:237], v[136:139], off
	s_nop 1
	v_pk_fma_f32 v[136:137], v[140:141], v[140:141], 0 op_sel_hi:[1,1,0]
	v_pk_fma_f32 v[138:139], v[142:143], v[142:143], 0 op_sel_hi:[1,1,0]
	v_lshlrev_b32_e32 v140, 16, v184
	v_and_b32_e32 v141, 0xffff0000, v184
	v_lshlrev_b32_e32 v142, 16, v185
	v_and_b32_e32 v143, 0xffff0000, v185
	v_lshlrev_b32_e32 v184, 16, v186
	v_and_b32_e32 v185, 0xffff0000, v186
	v_lshlrev_b32_e32 v186, 16, v187
	v_and_b32_e32 v187, 0xffff0000, v187
	v_pk_fma_f32 v[138:139], v[188:189], v[188:189], v[138:139]
	v_pk_fma_f32 v[136:137], v[190:191], v[190:191], v[136:137]
	v_pk_fma_f32 v[118:119], v[118:119], 0.5, v[142:143] op_sel_hi:[1,0,1]
	v_pk_fma_f32 v[116:117], v[116:117], 0.5, v[140:141] op_sel_hi:[1,0,1]
	v_pk_fma_f32 v[140:141], v[114:115], 0.5, v[186:187] op_sel_hi:[1,0,1]
	v_pk_fma_f32 v[142:143], v[112:113], 0.5, v[184:185] op_sel_hi:[1,0,1]
	v_cvt_pk_bf16_f32 v112, v116, v117
	v_cvt_pk_bf16_f32 v113, v118, v119
	s_nop 0
	v_cvt_pk_bf16_f32 v114, v142, v143
	v_cvt_pk_bf16_f32 v115, v140, v141
	global_store_dwordx4 v[236:237], v[112:115], off offset:256
	s_nop 1
	v_pk_fma_f32 v[112:113], v[116:117], v[116:117], v[136:137]
	v_pk_fma_f32 v[114:115], v[118:119], v[118:119], v[138:139]
	v_pk_fma_f32 v[112:113], v[142:143], v[142:143], v[112:113]
	v_pk_fma_f32 v[114:115], v[140:141], v[140:141], v[114:115]
	v_add_f32_e32 v112, v112, v113
	v_add_f32_e32 v113, v114, v115
	v_and_b32_e32 v114, 64, v248
	v_add_f32_e32 v113, v112, v113
	v_xor_b32_e32 v112, 16, v248
	v_add_u32_e32 v115, 64, v114
	v_cmp_lt_i32_e32 vcc, v112, v115
	s_nop 1
	v_cndmask_b32_e32 v112, v248, v112, vcc
	v_lshlrev_b32_e32 v112, 2, v112
	v_mov_b32_e32 v114, v113
	s_nop 1
	v_permlane16_swap_b32 v114, v113
	s_waitcnt lgkmcnt(0)
	v_add_f32_e32 v114, v113, v114
	v_xor_b32_e32 v113, 32, v248
	v_cmp_lt_i32_e32 vcc, v113, v115
	s_nop 1
	v_cndmask_b32_e32 v113, v248, v113, vcc
	v_lshlrev_b32_e32 v113, 2, v113
	v_mov_b32_e32 v115, v114
	s_nop 1
	v_permlane32_swap_b32 v115, v114
	s_and_saveexec_b64 s[52:53], s[6:7]
	s_cbranch_execz .LBB0_277
	v_lshlrev_b64 v[116:117], 6, v[234:235]
	v_lshl_add_u64 v[116:117], s[70:71], 0, v[116:117]
	v_lshl_add_u64 v[116:117], s[86:87], 2, v[116:117]
	s_lshl_b32 s76, s20, 2
	v_lshl_add_u64 v[116:117], v[116:117], 0, s[76:77]
	s_waitcnt lgkmcnt(0)
	v_add_f32_e32 v114, v114, v115
	global_store_dword v[116:117], v114, off

.LBB0_291:
	s_or_b64 exec, exec, s[52:53]
	s_and_b64 vcc, exec, s[8:9]
	s_mov_b64 s[8:9], -1
	s_cbranch_vccnz .LBB0_260
	s_andn2_b64 vcc, exec, s[78:79]
	s_cbranch_vccnz .LBB0_259
	s_branch .LBB0_259
.LBB0_294:
	s_waitcnt vmcnt(0)
	s_and_b64 vcc, exec, s[82:83]
	s_cbranch_vccz .Lua_1
	s_barrier

.Lzskip_2:
	s_and_b64 vcc, exec, s[82:83]
	s_cbranch_vccz .LBB0_432
.LBB0_432:
	s_lshl_b32 s15, s86, 8
	s_add_i32 s15, s15, s73
	v_or_b32_e32 v174, s15, v199
	v_or_b32_e32 v170, 16, v174
	v_or_b32_e32 v166, 32, v174
	v_or_b32_e32 v164, 48, v174
	s_mov_b64 s[6:7], -1
	s_cmp_gt_u32 s14, 13
	v_ashrrev_i32_e32 v175, 31, v174
	v_ashrrev_i32_e32 v171, 31, v170
	v_ashrrev_i32_e32 v167, 31, v166
	v_ashrrev_i32_e32 v165, 31, v164
	s_cbranch_scc1 .LBB0_437
	s_andn2_b64 vcc, exec, s[6:7]
	s_cbranch_vccz .LBB0_438

.LBB0_451:
	s_andn2_b64 vcc, exec, s[26:27]
	s_cbranch_vccnz .LBB0_424
	s_branch .LBB0_424
.LBB0_453:
	s_waitcnt vmcnt(0)
	v_readlane_b32 s24, v254, 53
	v_readlane_b32 s26, v254, 55
	v_readlane_b32 s25, v254, 54
	v_readlane_b32 s27, v254, 56
	s_and_b64 vcc, exec, s[82:83]
	s_cbranch_vccz .Lua_2
	s_barrier

.Lzskip_3:
	s_and_b64 vcc, exec, s[48:49]
	s_cbranch_vccz .LBB0_996
.LBB0_996:
	v_lshl_or_b32 v204, s10, 8, v244
	v_lshl_add_u32 v234, s80, 8, v242
	v_ashrrev_i32_e32 v205, 31, v204
	v_lshlrev_b64 v[236:237], 1, v[204:205]
	v_ashrrev_i32_e32 v235, 31, v234
	v_lshl_add_u64 v[124:125], s[12:13], 0, v[236:237]
	v_lshlrev_b64 v[238:239], 11, v[234:235]
	v_lshl_add_u64 v[120:121], v[124:125], 0, v[238:239]
	global_load_dwordx4 v[188:191], v[120:121], off
	global_load_dwordx4 v[184:187], v[120:121], off offset:256
	v_or_b32_e32 v230, 16, v234
	v_ashrrev_i32_e32 v231, 31, v230
	v_or_b32_e32 v226, 32, v234
	v_lshlrev_b64 v[232:233], 11, v[230:231]
	v_ashrrev_i32_e32 v227, 31, v226
	v_or_b32_e32 v222, 48, v234
	v_lshl_add_u64 v[120:121], v[124:125], 0, v[232:233]
	v_lshlrev_b64 v[228:229], 11, v[226:227]
	v_ashrrev_i32_e32 v223, 31, v222
	v_add_u32_e32 v218, 0x80, v234
	global_load_dwordx4 v[180:183], v[120:121], off
	global_load_dwordx4 v[176:179], v[120:121], off offset:256
	v_lshl_add_u64 v[120:121], v[124:125], 0, v[228:229]
	v_lshlrev_b64 v[224:225], 11, v[222:223]
	v_ashrrev_i32_e32 v219, 31, v218
	v_add_u32_e32 v214, 0x90, v234
	global_load_dwordx4 v[172:175], v[120:121], off
	global_load_dwordx4 v[168:171], v[120:121], off offset:256
	v_lshl_add_u64 v[120:121], v[124:125], 0, v[224:225]
	v_lshlrev_b64 v[220:221], 11, v[218:219]
	v_ashrrev_i32_e32 v215, 31, v214
	v_add_u32_e32 v210, 0xa0, v234
	v_add_u32_e32 v206, 0xb0, v234
	global_load_dwordx4 v[164:167], v[120:121], off
	global_load_dwordx4 v[160:163], v[120:121], off offset:256
	v_lshl_add_u64 v[120:121], v[124:125], 0, v[220:221]
	v_lshlrev_b64 v[216:217], 11, v[214:215]
	v_ashrrev_i32_e32 v211, 31, v210
	v_ashrrev_i32_e32 v207, 31, v206
	global_load_dwordx4 v[156:159], v[120:121], off
	global_load_dwordx4 v[152:155], v[120:121], off offset:256
	v_lshl_add_u64 v[120:121], v[124:125], 0, v[216:217]
	v_lshlrev_b64 v[212:213], 11, v[210:211]
	v_lshlrev_b64 v[208:209], 11, v[206:207]
	global_load_dwordx4 v[148:151], v[120:121], off
	global_load_dwordx4 v[144:147], v[120:121], off offset:256
	v_lshl_add_u64 v[120:121], v[124:125], 0, v[212:213]
	v_lshl_add_u64 v[124:125], v[124:125], 0, v[208:209]
	global_load_dwordx4 v[128:131], v[120:121], off
	s_nop 0
	global_load_dwordx4 v[120:123], v[120:121], off offset:256
	s_nop 0
	global_load_dwordx4 v[132:135], v[124:125], off
	s_nop 0
	global_load_dwordx4 v[124:127], v[124:125], off offset:256
	v_lshl_add_u64 v[238:239], s[12:13], 0, v[238:239]
	v_lshl_add_u64 v[236:237], v[238:239], 0, v[236:237]
	s_lshl_b32 s80, s10, 2
	s_ashr_i32 s81, s80, 31
	s_waitcnt vmcnt(0)
	v_lshlrev_b32_e32 v250, 16, v188
	v_and_b32_e32 v251, 0xffff0000, v188
	v_lshlrev_b32_e32 v188, 16, v189
	v_and_b32_e32 v189, 0xffff0000, v189
	v_lshlrev_b32_e32 v252, 16, v190
	v_and_b32_e32 v253, 0xffff0000, v190
	v_lshlrev_b32_e32 v190, 16, v191
	v_and_b32_e32 v191, 0xffff0000, v191
	v_pk_add_f32 v[142:143], v[142:143], v[188:189]
	v_pk_add_f32 v[140:141], v[140:141], v[250:251]
	v_pk_add_f32 v[188:189], v[138:139], v[190:191]
	v_pk_add_f32 v[190:191], v[136:137], v[252:253]
	v_cvt_pk_bf16_f32 v136, v140, v141
	v_cvt_pk_bf16_f32 v137, v142, v143
	s_nop 0
	v_cvt_pk_bf16_f32 v138, v190, v191
	v_cvt_pk_bf16_f32 v139, v188, v189
	global_store_dwordx4 v[236:237], v[136:139], off
	s_nop 1
	v_pk_fma_f32 v[136:137], v[140:141], v[140:141], 0 op_sel_hi:[1,1,0]
	v_pk_fma_f32 v[138:139], v[142:143], v[142:143], 0 op_sel_hi:[1,1,0]
	v_lshlrev_b32_e32 v140, 16, v184
	v_and_b32_e32 v141, 0xffff0000, v184
	v_lshlrev_b32_e32 v142, 16, v185
	v_and_b32_e32 v143, 0xffff0000, v185
	v_lshlrev_b32_e32 v184, 16, v186
	v_and_b32_e32 v185, 0xffff0000, v186
	v_lshlrev_b32_e32 v186, 16, v187
	v_and_b32_e32 v187, 0xffff0000, v187
	v_pk_fma_f32 v[138:139], v[188:189], v[188:189], v[138:139]
	v_pk_fma_f32 v[136:137], v[190:191], v[190:191], v[136:137]
	v_pk_add_f32 v[118:119], v[118:119], v[142:143]
	v_pk_add_f32 v[116:117], v[116:117], v[140:141]
	v_pk_add_f32 v[140:141], v[114:115], v[186:187]
	v_pk_add_f32 v[142:143], v[112:113], v[184:185]
	v_cvt_pk_bf16_f32 v112, v116, v117
	v_cvt_pk_bf16_f32 v113, v118, v119
	s_nop 0
	v_cvt_pk_bf16_f32 v114, v142, v143
	v_cvt_pk_bf16_f32 v115, v140, v141
	global_store_dwordx4 v[236:237], v[112:115], off offset:256
	s_nop 1
	v_pk_fma_f32 v[112:113], v[116:117], v[116:117], v[136:137]
	v_pk_fma_f32 v[114:115], v[118:119], v[118:119], v[138:139]
	v_pk_fma_f32 v[112:113], v[142:143], v[142:143], v[112:113]
	v_pk_fma_f32 v[114:115], v[140:141], v[140:141], v[114:115]
	v_add_f32_e32 v112, v112, v113
	v_add_f32_e32 v113, v114, v115
	v_and_b32_e32 v114, 64, v248
	v_add_f32_e32 v113, v112, v113
	v_xor_b32_e32 v112, 16, v248
	v_add_u32_e32 v115, 64, v114
	v_cmp_lt_i32_e32 vcc, v112, v115
	s_nop 1
	v_cndmask_b32_e32 v112, v248, v112, vcc
	v_lshlrev_b32_e32 v112, 2, v112
	v_mov_b32_e32 v114, v113
	s_nop 1
	v_permlane16_swap_b32 v114, v113
	s_waitcnt lgkmcnt(0)
	v_add_f32_e32 v114, v113, v114
	v_xor_b32_e32 v113, 32, v248
	v_cmp_lt_i32_e32 vcc, v113, v115
	s_nop 1
	v_cndmask_b32_e32 v113, v248, v113, vcc
	v_lshlrev_b32_e32 v113, 2, v113
	v_mov_b32_e32 v115, v114
	s_nop 1
	v_permlane32_swap_b32 v115, v114
	s_and_saveexec_b64 s[54:55], s[4:5]
	s_cbranch_execz .LBB0_998
	v_lshlrev_b64 v[116:117], 6, v[234:235]
	v_lshl_add_u64 v[116:117], s[70:71], 0, v[116:117]
	v_lshl_add_u64 v[116:117], s[80:81], 2, v[116:117]
	s_lshl_b32 s10, s20, 2
	v_lshl_add_u64 v[116:117], v[116:117], 0, s[10:11]
	s_waitcnt lgkmcnt(0)
	v_add_f32_e32 v114, v114, v115
	global_store_dword v[116:117], v114, off

.LBB0_1012:
	s_or_b64 exec, exec, s[54:55]
	s_andn2_b64 vcc, exec, s[6:7]
	s_mov_b64 s[6:7], -1
	s_cbranch_vccnz .LBB0_985
	s_andn2_b64 vcc, exec, s[44:45]
	s_cbranch_vccnz .LBB0_984
	s_branch .LBB0_984
.LBB0_1015:
	s_waitcnt vmcnt(0)
	s_and_b64 vcc, exec, s[48:49]
	s_cbranch_vccz .Lua_3
	s_barrier

.Lzskip_4:
	s_and_b64 vcc, exec, s[44:45]
	s_cbranch_vccz .LBB0_1151
.LBB0_1151:
	v_lshl_add_u32 v160, s76, 8, v170
	v_or_b32_e32 v156, 16, v160
	v_or_b32_e32 v152, 32, v160
	v_or_b32_e32 v150, 48, v160
	s_mov_b64 s[54:55], -1
	s_cmp_gt_u32 s57, 13
	v_ashrrev_i32_e32 v161, 31, v160
	v_ashrrev_i32_e32 v157, 31, v156
	v_ashrrev_i32_e32 v153, 31, v152
	v_ashrrev_i32_e32 v151, 31, v150
	v_add_u32_e32 v164, 0x80, v160
	s_cbranch_scc0 .LBB0_1153
	v_lshlrev_b64 v[146:147], 6, v[160:161]
	v_lshlrev_b64 v[148:149], 6, v[156:157]
	v_lshl_add_u64 v[146:147], v[138:139], 0, v[146:147]
	v_lshl_add_u64 v[148:149], v[138:139], 0, v[148:149]
	global_load_dwordx4 v[178:181], v[146:147], off
	global_load_dwordx4 v[182:185], v[148:149], off
	v_lshlrev_b64 v[148:149], 6, v[152:153]
	v_lshl_add_u64 v[148:149], v[138:139], 0, v[148:149]
	global_load_dwordx4 v[186:189], v[148:149], off
	v_lshlrev_b64 v[148:149], 6, v[150:151]
	v_lshl_add_u64 v[148:149], v[138:139], 0, v[148:149]
	s_movk_i32 s47, 0x2000
	global_load_dwordx4 v[190:193], v[148:149], off
	v_add_co_u32_e32 v148, vcc, s47, v146
	v_add_u32_e32 v146, 0x80, v160
	s_nop 0
	v_addc_co_u32_e32 v149, vcc, 0, v147, vcc
	v_ashrrev_i32_e32 v147, 31, v146
	v_lshlrev_b64 v[154:155], 6, v[146:147]
	v_lshl_add_u64 v[154:155], v[138:139], 0, v[154:155]
	global_load_dwordx4 v[194:197], v[148:149], off offset:2048
	global_load_dwordx4 v[198:201], v[154:155], off
	global_load_dwordx4 v[202:205], v[148:149], off offset:1024
	global_load_dwordx4 v[206:209], v[148:149], off offset:3072
	v_xor_b32_e32 v148, 16, v168
	v_xor_b32_e32 v149, 32, v168
	v_cmp_lt_i32_e32 vcc, v148, v169
	s_mov_b64 s[54:55], 0
	s_waitcnt vmcnt(0)
	v_mov_b32_e32 v154, v183
	v_cndmask_b32_e32 v148, v168, v148, vcc
	v_cmp_lt_i32_e32 vcc, v149, v169
	v_lshlrev_b32_e32 v165, 2, v148
	v_mov_b32_e32 v148, v179
	v_cndmask_b32_e32 v149, v168, v149, vcc
	v_lshlrev_b32_e32 v210, 2, v149
	v_mov_b32_e32 v149, v180
	v_mov_b32_e32 v179, v181
	v_mov_b32_e32 v155, v184
	v_mov_b32_e32 v183, v185
	v_pk_add_f32 v[148:149], v[148:149], v[178:179]
	v_pk_add_f32 v[154:155], v[154:155], v[182:183]
	v_add_f32_e32 v178, v148, v149
	v_mov_b32_e32 v158, v187
	v_mov_b32_e32 v148, v199
	v_mov_b32_e32 v149, v200
	v_mov_b32_e32 v199, v201
	v_mov_b32_e32 v159, v188
	v_mov_b32_e32 v187, v189
	v_mov_b32_e32 v162, v191
	v_mov_b32_e32 v163, v192
	v_mov_b32_e32 v191, v193
	v_add_f32_e32 v179, v154, v155
	v_mov_b32_e32 v154, v203
	v_mov_b32_e32 v155, v204
	v_mov_b32_e32 v203, v205
	v_pk_add_f32 v[148:149], v[148:149], v[198:199]
	v_pk_add_f32 v[158:159], v[158:159], v[186:187]
	v_pk_add_f32 v[162:163], v[162:163], v[190:191]
	v_mov_b32_e32 v166, v195
	v_mov_b32_e32 v167, v196
	v_mov_b32_e32 v195, v197
	v_pk_add_f32 v[154:155], v[154:155], v[202:203]
	v_add_f32_e32 v148, v148, v149
	v_add_f32_e32 v180, v158, v159
	v_add_f32_e32 v162, v162, v163
	v_pk_add_f32 v[158:159], v[166:167], v[194:195]
	ds_bpermute_b32 v163, v165, v178
	v_add_f32_e32 v149, v154, v155
	ds_bpermute_b32 v154, v165, v148
	ds_bpermute_b32 v166, v165, v179
	ds_bpermute_b32 v167, v165, v180
	v_add_f32_e32 v158, v158, v159
	ds_bpermute_b32 v159, v165, v149
	s_waitcnt lgkmcnt(4)
	v_add_f32_e32 v163, v178, v163
	s_waitcnt lgkmcnt(3)
	v_add_f32_e32 v148, v148, v154
	s_waitcnt lgkmcnt(2)
	v_add_f32_e32 v166, v179, v166
	s_waitcnt lgkmcnt(1)
	v_add_f32_e32 v167, v180, v167
	ds_bpermute_b32 v178, v210, v163
	s_waitcnt lgkmcnt(1)
	v_add_f32_e32 v159, v149, v159
	ds_bpermute_b32 v149, v210, v148
	ds_bpermute_b32 v179, v210, v166
	ds_bpermute_b32 v180, v210, v167
	s_waitcnt lgkmcnt(3)
	v_add_f32_e32 v154, v163, v178
	v_fmamk_f32 v154, v154, 0x3a800000, v177
	s_waitcnt lgkmcnt(2)
	v_add_f32_e32 v148, v148, v149
	s_waitcnt lgkmcnt(1)
	v_add_f32_e32 v163, v166, v179
	s_waitcnt lgkmcnt(0)
	v_add_f32_e32 v166, v167, v180
	v_fmamk_f32 v148, v148, 0x3a800000, v177
	v_fmamk_f32 v178, v166, 0x3a800000, v177
	v_rsq_f32_e32 v166, v154
	v_rsq_f32_e32 v154, v148
	v_mov_b32_e32 v148, v207
	v_mov_b32_e32 v149, v208
	v_mov_b32_e32 v207, v209
	v_pk_add_f32 v[148:149], v[148:149], v[206:207]
	ds_bpermute_b32 v181, v165, v162
	v_add_f32_e32 v148, v148, v149
	ds_bpermute_b32 v155, v165, v158
	ds_bpermute_b32 v182, v210, v159
	ds_bpermute_b32 v149, v165, v148
	s_waitcnt lgkmcnt(3)
	v_add_f32_e32 v162, v162, v181
	ds_bpermute_b32 v181, v210, v162
	s_waitcnt lgkmcnt(3)
	v_add_f32_e32 v158, v158, v155
	s_waitcnt lgkmcnt(2)
	v_add_f32_e32 v159, v159, v182
	s_waitcnt lgkmcnt(1)
	v_add_f32_e32 v149, v148, v149
	ds_bpermute_b32 v165, v210, v158
	v_fmamk_f32 v155, v159, 0x3a800000, v177
	ds_bpermute_b32 v159, v210, v149
	s_waitcnt lgkmcnt(2)
	v_add_f32_e32 v162, v162, v181
	v_fmamk_f32 v163, v163, 0x3a800000, v177
	s_waitcnt lgkmcnt(1)
	v_add_f32_e32 v148, v158, v165
	v_fmamk_f32 v179, v162, 0x3a800000, v177
	s_waitcnt lgkmcnt(0)
	v_add_f32_e32 v149, v149, v159
	v_fmamk_f32 v148, v148, 0x3a800000, v177
	v_fmamk_f32 v149, v149, 0x3a800000, v177
	v_rsq_f32_e32 v167, v163
	v_rsq_f32_e32 v162, v178
	v_rsq_f32_e32 v163, v179
	v_rsq_f32_e32 v155, v155
	v_rsq_f32_e32 v148, v148
	v_rsq_f32_e32 v149, v149
	v_mov_b64_e32 v[158:159], v[146:147]

.LBB0_1155:
	s_waitcnt lgkmcnt(0)
	v_mul_f32_e32 v164, 0xbfb8aa3b, v166
	v_mul_f32_e32 v147, v166, v166
	v_pk_mul_f32 v[178:179], v[126:127], v[164:165] op_sel_hi:[1,0]
	v_pk_mul_f32 v[122:123], v[126:127], v[122:123]
	v_pk_mul_f32 v[126:127], v[116:117], v[164:165] op_sel_hi:[1,0]
	v_rcp_f32_e32 v166, v147
	v_pk_mul_f32 v[180:181], v[124:125], v[164:165] op_sel_hi:[1,0]
	v_exp_f32_e32 v126, v126
	v_exp_f32_e32 v127, v127
	v_exp_f32_e32 v180, v180
	v_exp_f32_e32 v178, v178
	v_exp_f32_e32 v179, v179
	v_exp_f32_e32 v181, v181
	v_pk_mul_f32 v[120:121], v[124:125], v[120:121]
	v_pk_mul_f32 v[124:125], v[118:119], v[164:165] op_sel_hi:[1,0]
	v_pk_fma_f32 v[126:127], v[126:127], v[166:167], v[166:167] op_sel_hi:[1,0,0]
	v_exp_f32_e32 v124, v124
	v_exp_f32_e32 v125, v125
	v_pk_fma_f32 v[178:179], v[178:179], v[166:167], v[166:167] op_sel_hi:[1,0,0]
	v_pk_fma_f32 v[180:181], v[180:181], v[166:167], v[166:167] op_sel_hi:[1,0,0]
	v_rcp_f32_e32 v126, v126
	v_rcp_f32_e32 v127, v127
	v_rcp_f32_e32 v180, v180
	v_rcp_f32_e32 v181, v181
	v_rcp_f32_e32 v178, v178
	v_rcp_f32_e32 v179, v179
	v_pk_fma_f32 v[124:125], v[124:125], v[166:167], v[166:167] op_sel_hi:[1,0,0]
	v_pk_mul_f32 v[112:113], v[116:117], v[112:113]
	v_rcp_f32_e32 v124, v124
	v_rcp_f32_e32 v125, v125
	v_pk_mul_f32 v[112:113], v[112:113], v[126:127]
	v_pk_mul_f32 v[122:123], v[122:123], v[178:179]
	v_pk_mul_f32 v[120:121], v[120:121], v[180:181]
	v_pk_mul_f32 v[114:115], v[118:119], v[114:115]
	v_cvt_pk_bf16_f32 v116, v120, v121
	v_cvt_pk_bf16_f32 v117, v122, v123
	v_cvt_pk_bf16_f32 v118, v112, v113
	v_mov_b64_e32 v[112:113], s[64:65]
	v_pk_mul_f32 v[114:115], v[114:115], v[124:125]
	v_mad_u64_u32 v[120:121], s[54:55], v160, s27, v[112:113]
	v_cvt_pk_bf16_f32 v119, v114, v115
	v_mov_b32_e32 v114, v121
	v_mul_f32_e32 v122, 0xbfb8aa3b, v167
	v_mul_f32_e32 v123, v167, v167
	v_mad_u64_u32 v[114:115], s[54:55], v161, s27, v[114:115]
	v_pk_mul_f32 v[126:127], v[110:111], v[122:123] op_sel_hi:[1,0]
	v_pk_mul_f32 v[160:161], v[108:109], v[122:123] op_sel_hi:[1,0]
	v_pk_mul_f32 v[106:107], v[110:111], v[106:107]
	v_pk_mul_f32 v[104:105], v[108:109], v[104:105]
	v_pk_mul_f32 v[108:109], v[102:103], v[122:123] op_sel_hi:[1,0]
	v_pk_mul_f32 v[110:111], v[100:101], v[122:123] op_sel_hi:[1,0]
	v_rcp_f32_e32 v124, v123
	v_exp_f32_e32 v110, v110
	v_exp_f32_e32 v108, v108
	v_exp_f32_e32 v109, v109
	v_exp_f32_e32 v111, v111
	v_lshl_or_b32 v182, s56, 7, v173
	v_exp_f32_e32 v160, v160
	v_exp_f32_e32 v126, v126
	v_exp_f32_e32 v127, v127
	v_exp_f32_e32 v161, v161
	v_ashrrev_i32_e32 v183, 31, v182
	v_mov_b32_e32 v121, v114
	v_lshlrev_b64 v[114:115], 1, v[182:183]
	v_lshl_add_u64 v[120:121], v[120:121], 0, v[114:115]
	v_pk_fma_f32 v[108:109], v[108:109], v[124:125], v[124:125] op_sel_hi:[1,0,0]
	v_pk_fma_f32 v[110:111], v[110:111], v[124:125], v[124:125] op_sel_hi:[1,0,0]
	global_store_dwordx4 v[120:121], v[116:119], off
	v_rcp_f32_e32 v110, v110
	v_rcp_f32_e32 v108, v108
	v_pk_fma_f32 v[116:117], v[126:127], v[124:125], v[124:125] op_sel_hi:[1,0,0]
	v_pk_fma_f32 v[118:119], v[160:161], v[124:125], v[124:125] op_sel_hi:[1,0,0]
	v_rcp_f32_e32 v109, v109
	v_rcp_f32_e32 v111, v111
	v_rcp_f32_e32 v118, v118
	v_rcp_f32_e32 v119, v119
	v_rcp_f32_e32 v116, v116
	v_rcp_f32_e32 v117, v117
	v_pk_mul_f32 v[98:99], v[102:103], v[98:99]
	v_pk_mul_f32 v[96:97], v[100:101], v[96:97]
	v_pk_mul_f32 v[100:101], v[98:99], v[108:109]
	v_pk_mul_f32 v[98:99], v[96:97], v[110:111]
	v_pk_mul_f32 v[106:107], v[106:107], v[116:117]
	v_pk_mul_f32 v[104:105], v[104:105], v[118:119]
	v_pk_mul_f32 v[90:91], v[94:95], v[90:91]
	v_cvt_pk_bf16_f32 v96, v104, v105
	v_cvt_pk_bf16_f32 v97, v106, v107
	v_cvt_pk_bf16_f32 v98, v98, v99
	v_cvt_pk_bf16_f32 v99, v100, v101
	v_mad_u64_u32 v[100:101], s[54:55], v156, s27, v[112:113]
	v_mul_f32_e32 v102, 0xbfb8aa3b, v162
	v_mul_f32_e32 v103, v162, v162
	v_pk_mul_f32 v[106:107], v[94:95], v[102:103] op_sel_hi:[1,0]
	v_pk_mul_f32 v[108:109], v[92:93], v[102:103] op_sel_hi:[1,0]
	v_pk_mul_f32 v[88:89], v[92:93], v[88:89]
	v_pk_mul_f32 v[92:93], v[86:87], v[102:103] op_sel_hi:[1,0]
	v_pk_mul_f32 v[94:95], v[84:85], v[102:103] op_sel_hi:[1,0]
	v_rcp_f32_e32 v104, v103
	v_exp_f32_e32 v94, v94
	v_exp_f32_e32 v92, v92
	v_exp_f32_e32 v93, v93
	v_exp_f32_e32 v95, v95
	v_exp_f32_e32 v108, v108
	v_exp_f32_e32 v106, v106
	v_exp_f32_e32 v107, v107
	v_exp_f32_e32 v109, v109
	v_lshl_add_u64 v[100:101], v[100:101], 0, v[114:115]
	v_pk_fma_f32 v[92:93], v[92:93], v[104:105], v[104:105] op_sel_hi:[1,0,0]
	v_pk_fma_f32 v[94:95], v[94:95], v[104:105], v[104:105] op_sel_hi:[1,0,0]
	global_store_dwordx4 v[100:101], v[96:99], off
	v_rcp_f32_e32 v94, v94
	v_rcp_f32_e32 v92, v92
	v_pk_fma_f32 v[96:97], v[106:107], v[104:105], v[104:105] op_sel_hi:[1,0,0]
	v_pk_fma_f32 v[98:99], v[108:109], v[104:105], v[104:105] op_sel_hi:[1,0,0]
	v_rcp_f32_e32 v93, v93
	v_rcp_f32_e32 v95, v95
	v_rcp_f32_e32 v98, v98
	v_rcp_f32_e32 v99, v99
	v_rcp_f32_e32 v96, v96
	v_rcp_f32_e32 v97, v97
	v_pk_mul_f32 v[82:83], v[86:87], v[82:83]
	v_pk_mul_f32 v[80:81], v[84:85], v[80:81]
	v_pk_mul_f32 v[84:85], v[82:83], v[92:93]
	v_pk_mul_f32 v[82:83], v[80:81], v[94:95]
	v_pk_mul_f32 v[90:91], v[90:91], v[96:97]
	v_pk_mul_f32 v[88:89], v[88:89], v[98:99]
	v_pk_mul_f32 v[74:75], v[78:79], v[74:75]
	v_cvt_pk_bf16_f32 v80, v88, v89
	v_cvt_pk_bf16_f32 v81, v90, v91
	v_cvt_pk_bf16_f32 v82, v82, v83
	v_cvt_pk_bf16_f32 v83, v84, v85
	v_mad_u64_u32 v[84:85], s[54:55], v152, s27, v[112:113]
	v_mul_f32_e32 v86, 0xbfb8aa3b, v163
	v_mul_f32_e32 v87, v163, v163
	v_pk_mul_f32 v[90:91], v[78:79], v[86:87] op_sel_hi:[1,0]
	v_pk_mul_f32 v[92:93], v[76:77], v[86:87] op_sel_hi:[1,0]
	v_pk_mul_f32 v[72:73], v[76:77], v[72:73]
	v_pk_mul_f32 v[76:77], v[70:71], v[86:87] op_sel_hi:[1,0]
	v_pk_mul_f32 v[78:79], v[68:69], v[86:87] op_sel_hi:[1,0]
	v_rcp_f32_e32 v88, v87
	v_exp_f32_e32 v78, v78
	v_exp_f32_e32 v76, v76
	v_exp_f32_e32 v77, v77
	v_exp_f32_e32 v79, v79
	v_exp_f32_e32 v92, v92
	v_exp_f32_e32 v90, v90
	v_exp_f32_e32 v91, v91
	v_exp_f32_e32 v93, v93
	v_lshl_add_u64 v[84:85], v[84:85], 0, v[114:115]
	v_pk_fma_f32 v[76:77], v[76:77], v[88:89], v[88:89] op_sel_hi:[1,0,0]
	v_pk_fma_f32 v[78:79], v[78:79], v[88:89], v[88:89] op_sel_hi:[1,0,0]
	global_store_dwordx4 v[84:85], v[80:83], off
	v_rcp_f32_e32 v78, v78
	v_rcp_f32_e32 v76, v76
	v_pk_fma_f32 v[80:81], v[90:91], v[88:89], v[88:89] op_sel_hi:[1,0,0]
	v_pk_fma_f32 v[82:83], v[92:93], v[88:89], v[88:89] op_sel_hi:[1,0,0]
	v_rcp_f32_e32 v77, v77
	v_rcp_f32_e32 v79, v79
	v_rcp_f32_e32 v82, v82
	v_rcp_f32_e32 v83, v83
	v_rcp_f32_e32 v80, v80
	v_rcp_f32_e32 v81, v81
	v_pk_mul_f32 v[66:67], v[70:71], v[66:67]
	v_pk_mul_f32 v[64:65], v[68:69], v[64:65]
	v_pk_mul_f32 v[68:69], v[66:67], v[76:77]
	v_pk_mul_f32 v[66:67], v[64:65], v[78:79]
	v_pk_mul_f32 v[74:75], v[74:75], v[80:81]
	v_pk_mul_f32 v[72:73], v[72:73], v[82:83]
	v_pk_mul_f32 v[58:59], v[62:63], v[58:59]
	v_cvt_pk_bf16_f32 v64, v72, v73
	v_cvt_pk_bf16_f32 v65, v74, v75
	v_cvt_pk_bf16_f32 v66, v66, v67
	v_cvt_pk_bf16_f32 v67, v68, v69
	v_mad_u64_u32 v[68:69], s[54:55], v150, s27, v[112:113]
	v_mul_f32_e32 v70, 0xbfb8aa3b, v154
	v_mul_f32_e32 v71, v154, v154
	v_pk_mul_f32 v[74:75], v[62:63], v[70:71] op_sel_hi:[1,0]
	v_pk_mul_f32 v[76:77], v[60:61], v[70:71] op_sel_hi:[1,0]
	v_pk_mul_f32 v[56:57], v[60:61], v[56:57]
	v_pk_mul_f32 v[60:61], v[54:55], v[70:71] op_sel_hi:[1,0]
	v_pk_mul_f32 v[62:63], v[52:53], v[70:71] op_sel_hi:[1,0]
	v_rcp_f32_e32 v72, v71
	v_exp_f32_e32 v62, v62
	v_exp_f32_e32 v60, v60
	v_exp_f32_e32 v61, v61
	v_exp_f32_e32 v63, v63
	v_exp_f32_e32 v76, v76
	v_exp_f32_e32 v74, v74
	v_exp_f32_e32 v75, v75
	v_exp_f32_e32 v77, v77
	v_lshl_add_u64 v[68:69], v[68:69], 0, v[114:115]
	v_pk_fma_f32 v[60:61], v[60:61], v[72:73], v[72:73] op_sel_hi:[1,0,0]
	v_pk_fma_f32 v[62:63], v[62:63], v[72:73], v[72:73] op_sel_hi:[1,0,0]
	global_store_dwordx4 v[68:69], v[64:67], off
	v_rcp_f32_e32 v62, v62
	v_rcp_f32_e32 v60, v60
	v_pk_fma_f32 v[64:65], v[74:75], v[72:73], v[72:73] op_sel_hi:[1,0,0]
	v_pk_fma_f32 v[66:67], v[76:77], v[72:73], v[72:73] op_sel_hi:[1,0,0]
	v_rcp_f32_e32 v61, v61
	v_rcp_f32_e32 v63, v63
	v_rcp_f32_e32 v66, v66
	v_rcp_f32_e32 v67, v67
	v_rcp_f32_e32 v64, v64
	v_rcp_f32_e32 v65, v65
	v_pk_mul_f32 v[50:51], v[54:55], v[50:51]
	v_pk_mul_f32 v[48:49], v[52:53], v[48:49]
	v_pk_mul_f32 v[52:53], v[50:51], v[60:61]
	v_pk_mul_f32 v[50:51], v[48:49], v[62:63]
	v_pk_mul_f32 v[58:59], v[58:59], v[64:65]
	v_pk_mul_f32 v[56:57], v[56:57], v[66:67]
	v_pk_mul_f32 v[42:43], v[46:47], v[42:43]
	v_cvt_pk_bf16_f32 v48, v56, v57
	v_cvt_pk_bf16_f32 v49, v58, v59
	v_cvt_pk_bf16_f32 v50, v50, v51
	v_cvt_pk_bf16_f32 v51, v52, v53
	v_mad_u64_u32 v[52:53], s[54:55], v158, s27, v[112:113]
	v_mov_b32_e32 v54, v53
	v_mad_u64_u32 v[54:55], s[54:55], v159, s27, v[54:55]
	v_mov_b32_e32 v53, v54
	v_mul_f32_e32 v54, 0xbfb8aa3b, v155
	v_mul_f32_e32 v55, v155, v155
	v_pk_mul_f32 v[58:59], v[46:47], v[54:55] op_sel_hi:[1,0]
	v_pk_mul_f32 v[60:61], v[44:45], v[54:55] op_sel_hi:[1,0]
	v_pk_mul_f32 v[40:41], v[44:45], v[40:41]
	v_pk_mul_f32 v[44:45], v[38:39], v[54:55] op_sel_hi:[1,0]
	v_pk_mul_f32 v[46:47], v[36:37], v[54:55] op_sel_hi:[1,0]
	v_rcp_f32_e32 v56, v55
	v_exp_f32_e32 v46, v46
	v_exp_f32_e32 v44, v44
	v_exp_f32_e32 v45, v45
	v_exp_f32_e32 v47, v47
	v_exp_f32_e32 v60, v60
	v_exp_f32_e32 v58, v58
	v_exp_f32_e32 v59, v59
	v_exp_f32_e32 v61, v61
	v_lshl_add_u64 v[52:53], v[52:53], 0, v[114:115]
	v_pk_fma_f32 v[44:45], v[44:45], v[56:57], v[56:57] op_sel_hi:[1,0,0]
	v_pk_fma_f32 v[46:47], v[46:47], v[56:57], v[56:57] op_sel_hi:[1,0,0]
	global_store_dwordx4 v[52:53], v[48:51], off
	v_rcp_f32_e32 v46, v46
	v_rcp_f32_e32 v44, v44
	v_pk_fma_f32 v[48:49], v[58:59], v[56:57], v[56:57] op_sel_hi:[1,0,0]
	v_pk_fma_f32 v[50:51], v[60:61], v[56:57], v[56:57] op_sel_hi:[1,0,0]
	v_rcp_f32_e32 v45, v45
	v_rcp_f32_e32 v47, v47
	v_rcp_f32_e32 v50, v50
	v_rcp_f32_e32 v51, v51
	v_rcp_f32_e32 v48, v48
	v_rcp_f32_e32 v49, v49
	v_pk_mul_f32 v[34:35], v[38:39], v[34:35]
	v_pk_mul_f32 v[32:33], v[36:37], v[32:33]
	v_pk_mul_f32 v[36:37], v[34:35], v[44:45]
	v_pk_mul_f32 v[34:35], v[32:33], v[46:47]
	v_add_u32_e32 v38, 16, v146
	v_pk_mul_f32 v[42:43], v[42:43], v[48:49]
	v_pk_mul_f32 v[40:41], v[40:41], v[50:51]
	v_mul_f32_e32 v39, v148, v148
	v_cvt_pk_bf16_f32 v32, v40, v41
	v_cvt_pk_bf16_f32 v33, v42, v43
	v_cvt_pk_bf16_f32 v34, v34, v35
	v_cvt_pk_bf16_f32 v35, v36, v37
	v_mad_i64_i32 v[36:37], s[54:55], v38, s27, v[112:113]
	v_mul_f32_e32 v38, 0xbfb8aa3b, v148
	v_pk_mul_f32 v[42:43], v[30:31], v[38:39] op_sel_hi:[1,0]
	v_pk_mul_f32 v[44:45], v[28:29], v[38:39] op_sel_hi:[1,0]
	v_pk_mul_f32 v[26:27], v[30:31], v[26:27]
	v_pk_mul_f32 v[24:25], v[28:29], v[24:25]
	v_pk_mul_f32 v[28:29], v[22:23], v[38:39] op_sel_hi:[1,0]
	v_pk_mul_f32 v[30:31], v[20:21], v[38:39] op_sel_hi:[1,0]
	v_rcp_f32_e32 v40, v39
	v_exp_f32_e32 v30, v30
	v_exp_f32_e32 v28, v28
	v_exp_f32_e32 v29, v29
	v_exp_f32_e32 v31, v31
	v_exp_f32_e32 v44, v44
	v_exp_f32_e32 v42, v42
	v_exp_f32_e32 v43, v43
	v_exp_f32_e32 v45, v45
	v_lshl_add_u64 v[36:37], v[36:37], 0, v[114:115]
	v_pk_fma_f32 v[28:29], v[28:29], v[40:41], v[40:41] op_sel_hi:[1,0,0]
	v_pk_fma_f32 v[30:31], v[30:31], v[40:41], v[40:41] op_sel_hi:[1,0,0]
	global_store_dwordx4 v[36:37], v[32:35], off
	v_rcp_f32_e32 v30, v30
	v_rcp_f32_e32 v28, v28
	v_pk_fma_f32 v[32:33], v[42:43], v[40:41], v[40:41] op_sel_hi:[1,0,0]
	v_pk_fma_f32 v[34:35], v[44:45], v[40:41], v[40:41] op_sel_hi:[1,0,0]
	v_rcp_f32_e32 v29, v29
	v_rcp_f32_e32 v31, v31
	v_rcp_f32_e32 v34, v34
	v_rcp_f32_e32 v35, v35
	v_rcp_f32_e32 v32, v32
	v_rcp_f32_e32 v33, v33
	v_pk_mul_f32 v[18:19], v[22:23], v[18:19]
	v_pk_mul_f32 v[16:17], v[20:21], v[16:17]
	v_pk_mul_f32 v[20:21], v[18:19], v[28:29]
	v_pk_mul_f32 v[18:19], v[16:17], v[30:31]
	v_add_u32_e32 v22, 32, v146
	v_pk_mul_f32 v[26:27], v[26:27], v[32:33]
	v_pk_mul_f32 v[24:25], v[24:25], v[34:35]
	v_mul_f32_e32 v23, v149, v149
	v_cvt_pk_bf16_f32 v16, v24, v25
	v_cvt_pk_bf16_f32 v17, v26, v27
	v_cvt_pk_bf16_f32 v18, v18, v19
	v_cvt_pk_bf16_f32 v19, v20, v21
	v_mad_i64_i32 v[20:21], s[54:55], v22, s27, v[112:113]
	v_mul_f32_e32 v22, 0xbfb8aa3b, v149
	v_pk_mul_f32 v[26:27], v[14:15], v[22:23] op_sel_hi:[1,0]
	v_pk_mul_f32 v[28:29], v[12:13], v[22:23] op_sel_hi:[1,0]
	v_pk_mul_f32 v[10:11], v[14:15], v[10:11]
	v_pk_mul_f32 v[8:9], v[12:13], v[8:9]
	v_pk_mul_f32 v[12:13], v[6:7], v[22:23] op_sel_hi:[1,0]
	v_pk_mul_f32 v[14:15], v[4:5], v[22:23] op_sel_hi:[1,0]
	v_rcp_f32_e32 v24, v23
	v_exp_f32_e32 v14, v14
	v_exp_f32_e32 v12, v12
	v_exp_f32_e32 v13, v13
	v_exp_f32_e32 v15, v15
	v_exp_f32_e32 v28, v28
	v_exp_f32_e32 v26, v26
	v_exp_f32_e32 v27, v27
	v_exp_f32_e32 v29, v29
	v_lshl_add_u64 v[20:21], v[20:21], 0, v[114:115]
	v_pk_fma_f32 v[12:13], v[12:13], v[24:25], v[24:25] op_sel_hi:[1,0,0]
	v_pk_fma_f32 v[14:15], v[14:15], v[24:25], v[24:25] op_sel_hi:[1,0,0]
	global_store_dwordx4 v[20:21], v[16:19], off
	v_rcp_f32_e32 v14, v14
	v_rcp_f32_e32 v12, v12
	v_pk_fma_f32 v[16:17], v[26:27], v[24:25], v[24:25] op_sel_hi:[1,0,0]
	v_pk_fma_f32 v[18:19], v[28:29], v[24:25], v[24:25] op_sel_hi:[1,0,0]
	v_rcp_f32_e32 v13, v13
	v_rcp_f32_e32 v15, v15
	v_rcp_f32_e32 v18, v18
	v_rcp_f32_e32 v19, v19
	v_rcp_f32_e32 v16, v16
	v_rcp_f32_e32 v17, v17
	v_pk_mul_f32 v[2:3], v[6:7], v[2:3]
	v_pk_mul_f32 v[0:1], v[4:5], v[0:1]
	v_pk_mul_f32 v[4:5], v[2:3], v[12:13]
	v_pk_mul_f32 v[2:3], v[0:1], v[14:15]
	v_add_u32_e32 v6, 48, v146
	v_pk_mul_f32 v[10:11], v[10:11], v[16:17]
	v_pk_mul_f32 v[8:9], v[8:9], v[18:19]
	s_andn2_b64 vcc, exec, s[4:5]
	v_cvt_pk_bf16_f32 v0, v8, v9
	v_cvt_pk_bf16_f32 v1, v10, v11
	v_cvt_pk_bf16_f32 v2, v2, v3
	v_cvt_pk_bf16_f32 v3, v4, v5
	v_mad_i64_i32 v[4:5], s[54:55], v6, s27, v[112:113]
	v_lshl_add_u64 v[4:5], v[4:5], 0, v[114:115]
	s_mov_b64 s[4:5], -1
	global_store_dwordx4 v[4:5], v[0:3], off
	s_cbranch_vccnz .LBB0_1144
	s_andn2_b64 vcc, exec, s[8:9]
	s_cbranch_vccnz .LBB0_1143
	s_branch .LBB0_1143
.LBB0_1158:
	s_waitcnt vmcnt(0)
	s_and_b64 vcc, exec, s[44:45]
	s_cbranch_vccz .Lua_4
	s_barrier

.Lzskip_5:
	s_and_b64 vcc, exec, s[50:51]
	s_cbranch_vccz .LBB0_1302
.LBB0_1302:
	v_lshl_or_b32 v204, s44, 8, v244
	v_lshl_add_u32 v234, s54, 8, v242
	v_ashrrev_i32_e32 v205, 31, v204
	v_lshlrev_b64 v[236:237], 1, v[204:205]
	v_ashrrev_i32_e32 v235, 31, v234
	v_lshl_add_u64 v[124:125], s[12:13], 0, v[236:237]
	v_lshlrev_b64 v[238:239], 11, v[234:235]
	v_lshl_add_u64 v[120:121], v[124:125], 0, v[238:239]
	global_load_dwordx4 v[188:191], v[120:121], off
	global_load_dwordx4 v[184:187], v[120:121], off offset:256
	v_or_b32_e32 v230, 16, v234
	v_ashrrev_i32_e32 v231, 31, v230
	v_or_b32_e32 v226, 32, v234
	v_lshlrev_b64 v[232:233], 11, v[230:231]
	v_ashrrev_i32_e32 v227, 31, v226
	v_or_b32_e32 v222, 48, v234
	v_lshl_add_u64 v[120:121], v[124:125], 0, v[232:233]
	v_lshlrev_b64 v[228:229], 11, v[226:227]
	v_ashrrev_i32_e32 v223, 31, v222
	v_add_u32_e32 v218, 0x80, v234
	global_load_dwordx4 v[180:183], v[120:121], off
	global_load_dwordx4 v[176:179], v[120:121], off offset:256
	v_lshl_add_u64 v[120:121], v[124:125], 0, v[228:229]
	v_lshlrev_b64 v[224:225], 11, v[222:223]
	v_ashrrev_i32_e32 v219, 31, v218
	v_add_u32_e32 v214, 0x90, v234
	global_load_dwordx4 v[172:175], v[120:121], off
	global_load_dwordx4 v[168:171], v[120:121], off offset:256
	v_lshl_add_u64 v[120:121], v[124:125], 0, v[224:225]
	v_lshlrev_b64 v[220:221], 11, v[218:219]
	v_ashrrev_i32_e32 v215, 31, v214
	v_add_u32_e32 v210, 0xa0, v234
	v_add_u32_e32 v206, 0xb0, v234
	global_load_dwordx4 v[164:167], v[120:121], off
	global_load_dwordx4 v[160:163], v[120:121], off offset:256
	v_lshl_add_u64 v[120:121], v[124:125], 0, v[220:221]
	v_lshlrev_b64 v[216:217], 11, v[214:215]
	v_ashrrev_i32_e32 v211, 31, v210
	v_ashrrev_i32_e32 v207, 31, v206
	global_load_dwordx4 v[156:159], v[120:121], off
	global_load_dwordx4 v[152:155], v[120:121], off offset:256
	v_lshl_add_u64 v[120:121], v[124:125], 0, v[216:217]
	v_lshlrev_b64 v[212:213], 11, v[210:211]
	v_lshlrev_b64 v[208:209], 11, v[206:207]
	global_load_dwordx4 v[148:151], v[120:121], off
	global_load_dwordx4 v[144:147], v[120:121], off offset:256
	v_lshl_add_u64 v[120:121], v[124:125], 0, v[212:213]
	v_lshl_add_u64 v[124:125], v[124:125], 0, v[208:209]
	global_load_dwordx4 v[128:131], v[120:121], off
	s_nop 0
	global_load_dwordx4 v[120:123], v[120:121], off offset:256
	s_nop 0
	global_load_dwordx4 v[132:135], v[124:125], off
	s_nop 0
	global_load_dwordx4 v[124:127], v[124:125], off offset:256
	v_lshl_add_u64 v[238:239], s[12:13], 0, v[238:239]
	v_lshl_add_u64 v[236:237], v[238:239], 0, v[236:237]
	s_lshl_b32 s76, s44, 2
	s_ashr_i32 s77, s76, 31
	s_waitcnt vmcnt(0)
	v_lshlrev_b32_e32 v250, 16, v188
	v_and_b32_e32 v251, 0xffff0000, v188
	v_lshlrev_b32_e32 v188, 16, v189
	v_and_b32_e32 v189, 0xffff0000, v189
	v_lshlrev_b32_e32 v252, 16, v190
	v_and_b32_e32 v253, 0xffff0000, v190
	v_lshlrev_b32_e32 v190, 16, v191
	v_and_b32_e32 v191, 0xffff0000, v191
	v_pk_fma_f32 v[142:143], v[142:143], 0.5, v[188:189] op_sel_hi:[1,0,1]
	v_pk_fma_f32 v[140:141], v[140:141], 0.5, v[250:251] op_sel_hi:[1,0,1]
	v_pk_fma_f32 v[188:189], v[138:139], 0.5, v[190:191] op_sel_hi:[1,0,1]
	v_pk_fma_f32 v[190:191], v[136:137], 0.5, v[252:253] op_sel_hi:[1,0,1]
	v_cvt_pk_bf16_f32 v136, v140, v141
	v_cvt_pk_bf16_f32 v137, v142, v143
	s_nop 0
	v_cvt_pk_bf16_f32 v138, v190, v191
	v_cvt_pk_bf16_f32 v139, v188, v189
	global_store_dwordx4 v[236:237], v[136:139], off
	s_nop 1
	v_pk_fma_f32 v[136:137], v[140:141], v[140:141], 0 op_sel_hi:[1,1,0]
	v_pk_fma_f32 v[138:139], v[142:143], v[142:143], 0 op_sel_hi:[1,1,0]
	v_lshlrev_b32_e32 v140, 16, v184
	v_and_b32_e32 v141, 0xffff0000, v184
	v_lshlrev_b32_e32 v142, 16, v185
	v_and_b32_e32 v143, 0xffff0000, v185
	v_lshlrev_b32_e32 v184, 16, v186
	v_and_b32_e32 v185, 0xffff0000, v186
	v_lshlrev_b32_e32 v186, 16, v187
	v_and_b32_e32 v187, 0xffff0000, v187
	v_pk_fma_f32 v[138:139], v[188:189], v[188:189], v[138:139]
	v_pk_fma_f32 v[136:137], v[190:191], v[190:191], v[136:137]
	v_pk_fma_f32 v[118:119], v[118:119], 0.5, v[142:143] op_sel_hi:[1,0,1]
	v_pk_fma_f32 v[116:117], v[116:117], 0.5, v[140:141] op_sel_hi:[1,0,1]
	v_pk_fma_f32 v[140:141], v[114:115], 0.5, v[186:187] op_sel_hi:[1,0,1]
	v_pk_fma_f32 v[142:143], v[112:113], 0.5, v[184:185] op_sel_hi:[1,0,1]
	v_cvt_pk_bf16_f32 v112, v116, v117
	v_cvt_pk_bf16_f32 v113, v118, v119
	s_nop 0
	v_cvt_pk_bf16_f32 v114, v142, v143
	v_cvt_pk_bf16_f32 v115, v140, v141
	global_store_dwordx4 v[236:237], v[112:115], off offset:256
	s_nop 1
	v_pk_fma_f32 v[112:113], v[116:117], v[116:117], v[136:137]
	v_pk_fma_f32 v[114:115], v[118:119], v[118:119], v[138:139]
	v_pk_fma_f32 v[112:113], v[142:143], v[142:143], v[112:113]
	v_pk_fma_f32 v[114:115], v[140:141], v[140:141], v[114:115]
	v_add_f32_e32 v112, v112, v113
	v_add_f32_e32 v113, v114, v115
	v_and_b32_e32 v114, 64, v248
	v_add_f32_e32 v113, v112, v113
	v_xor_b32_e32 v112, 16, v248
	v_add_u32_e32 v115, 64, v114
	v_cmp_lt_i32_e32 vcc, v112, v115
	s_nop 1
	v_cndmask_b32_e32 v112, v248, v112, vcc
	v_lshlrev_b32_e32 v112, 2, v112
	v_mov_b32_e32 v114, v113
	s_nop 1
	v_permlane16_swap_b32 v114, v113
	s_waitcnt lgkmcnt(0)
	v_add_f32_e32 v114, v113, v114
	v_xor_b32_e32 v113, 32, v248
	v_cmp_lt_i32_e32 vcc, v113, v115
	s_nop 1
	v_cndmask_b32_e32 v113, v248, v113, vcc
	v_lshlrev_b32_e32 v113, 2, v113
	v_mov_b32_e32 v115, v114
	s_nop 1
	v_permlane32_swap_b32 v115, v114
	s_and_saveexec_b64 s[54:55], s[4:5]
	s_cbranch_execz .LBB0_1304
	v_lshlrev_b64 v[116:117], 6, v[234:235]
	v_lshl_add_u64 v[116:117], s[70:71], 0, v[116:117]
	v_lshl_add_u64 v[116:117], s[76:77], 2, v[116:117]
	s_lshl_b32 s44, s20, 2
	v_lshl_add_u64 v[116:117], v[116:117], 0, s[44:45]
	s_waitcnt lgkmcnt(0)
	v_add_f32_e32 v114, v114, v115
	global_store_dword v[116:117], v114, off

.LBB0_1318:
	s_or_b64 exec, exec, s[54:55]
	s_and_b64 vcc, exec, s[6:7]
	s_mov_b64 s[6:7], -1
	s_cbranch_vccnz .LBB0_1287
	s_andn2_b64 vcc, exec, s[46:47]
	s_cbranch_vccnz .LBB0_1286
	s_branch .LBB0_1286
.LBB0_1321:
	s_waitcnt vmcnt(0)
	s_and_b64 vcc, exec, s[50:51]
	s_cbranch_vccz .Lua_5
	s_barrier

.Lzskip_6:
	s_and_b64 vcc, exec, s[44:45]
	s_cbranch_vccz .LBB0_1457
.LBB0_1457:
	v_lshl_add_u32 v160, s76, 8, v170
	v_or_b32_e32 v156, 16, v160
	v_or_b32_e32 v152, 32, v160
	v_or_b32_e32 v150, 48, v160
	s_mov_b64 s[54:55], -1
	s_cmp_gt_u32 s57, 13
	v_ashrrev_i32_e32 v161, 31, v160
	v_ashrrev_i32_e32 v157, 31, v156
	v_ashrrev_i32_e32 v153, 31, v152
	v_ashrrev_i32_e32 v151, 31, v150
	v_add_u32_e32 v164, 0x80, v160
	s_cbranch_scc0 .LBB0_1459
	v_lshlrev_b64 v[146:147], 6, v[160:161]
	v_lshlrev_b64 v[148:149], 6, v[156:157]
	v_lshl_add_u64 v[146:147], v[138:139], 0, v[146:147]
	v_lshl_add_u64 v[148:149], v[138:139], 0, v[148:149]
	global_load_dwordx4 v[178:181], v[146:147], off
	global_load_dwordx4 v[182:185], v[148:149], off
	v_lshlrev_b64 v[148:149], 6, v[152:153]
	v_lshl_add_u64 v[148:149], v[138:139], 0, v[148:149]
	global_load_dwordx4 v[186:189], v[148:149], off
	v_lshlrev_b64 v[148:149], 6, v[150:151]
	v_lshl_add_u64 v[148:149], v[138:139], 0, v[148:149]
	s_movk_i32 s47, 0x2000
	global_load_dwordx4 v[190:193], v[148:149], off
	v_add_co_u32_e32 v148, vcc, s47, v146
	v_add_u32_e32 v146, 0x80, v160
	s_nop 0
	v_addc_co_u32_e32 v149, vcc, 0, v147, vcc
	v_ashrrev_i32_e32 v147, 31, v146
	v_lshlrev_b64 v[154:155], 6, v[146:147]
	v_lshl_add_u64 v[154:155], v[138:139], 0, v[154:155]
	global_load_dwordx4 v[194:197], v[148:149], off offset:2048
	global_load_dwordx4 v[198:201], v[154:155], off
	global_load_dwordx4 v[202:205], v[148:149], off offset:1024
	global_load_dwordx4 v[206:209], v[148:149], off offset:3072
	v_xor_b32_e32 v148, 16, v168
	v_xor_b32_e32 v149, 32, v168
	v_cmp_lt_i32_e32 vcc, v148, v169
	s_mov_b64 s[54:55], 0
	s_waitcnt vmcnt(0)
	v_mov_b32_e32 v154, v183
	v_cndmask_b32_e32 v148, v168, v148, vcc
	v_cmp_lt_i32_e32 vcc, v149, v169
	v_lshlrev_b32_e32 v165, 2, v148
	v_mov_b32_e32 v148, v179
	v_cndmask_b32_e32 v149, v168, v149, vcc
	v_lshlrev_b32_e32 v210, 2, v149
	v_mov_b32_e32 v149, v180
	v_mov_b32_e32 v179, v181
	v_mov_b32_e32 v155, v184
	v_mov_b32_e32 v183, v185
	v_pk_add_f32 v[148:149], v[148:149], v[178:179]
	v_pk_add_f32 v[154:155], v[154:155], v[182:183]
	v_add_f32_e32 v178, v148, v149
	v_mov_b32_e32 v158, v187
	v_mov_b32_e32 v148, v199
	v_mov_b32_e32 v149, v200
	v_mov_b32_e32 v199, v201
	v_mov_b32_e32 v159, v188
	v_mov_b32_e32 v187, v189
	v_mov_b32_e32 v162, v191
	v_mov_b32_e32 v163, v192
	v_mov_b32_e32 v191, v193
	v_add_f32_e32 v179, v154, v155
	v_mov_b32_e32 v154, v203
	v_mov_b32_e32 v155, v204
	v_mov_b32_e32 v203, v205
	v_pk_add_f32 v[148:149], v[148:149], v[198:199]
	v_pk_add_f32 v[158:159], v[158:159], v[186:187]
	v_pk_add_f32 v[162:163], v[162:163], v[190:191]
	v_mov_b32_e32 v166, v195
	v_mov_b32_e32 v167, v196
	v_mov_b32_e32 v195, v197
	v_pk_add_f32 v[154:155], v[154:155], v[202:203]
	v_add_f32_e32 v148, v148, v149
	v_add_f32_e32 v180, v158, v159
	v_add_f32_e32 v162, v162, v163
	v_pk_add_f32 v[158:159], v[166:167], v[194:195]
	ds_bpermute_b32 v163, v165, v178
	v_add_f32_e32 v149, v154, v155
	ds_bpermute_b32 v154, v165, v148
	ds_bpermute_b32 v166, v165, v179
	ds_bpermute_b32 v167, v165, v180
	v_add_f32_e32 v158, v158, v159
	ds_bpermute_b32 v159, v165, v149
	s_waitcnt lgkmcnt(4)
	v_add_f32_e32 v163, v178, v163
	s_waitcnt lgkmcnt(3)
	v_add_f32_e32 v148, v148, v154
	s_waitcnt lgkmcnt(2)
	v_add_f32_e32 v166, v179, v166
	s_waitcnt lgkmcnt(1)
	v_add_f32_e32 v167, v180, v167
	ds_bpermute_b32 v178, v210, v163
	s_waitcnt lgkmcnt(1)
	v_add_f32_e32 v159, v149, v159
	ds_bpermute_b32 v149, v210, v148
	ds_bpermute_b32 v179, v210, v166
	ds_bpermute_b32 v180, v210, v167
	s_waitcnt lgkmcnt(3)
	v_add_f32_e32 v154, v163, v178
	v_fmamk_f32 v154, v154, 0x3a800000, v177
	s_waitcnt lgkmcnt(2)
	v_add_f32_e32 v148, v148, v149
	s_waitcnt lgkmcnt(1)
	v_add_f32_e32 v163, v166, v179
	s_waitcnt lgkmcnt(0)
	v_add_f32_e32 v166, v167, v180
	v_fmamk_f32 v148, v148, 0x3a800000, v177
	v_fmamk_f32 v178, v166, 0x3a800000, v177
	v_rsq_f32_e32 v166, v154
	v_rsq_f32_e32 v154, v148
	v_mov_b32_e32 v148, v207
	v_mov_b32_e32 v149, v208
	v_mov_b32_e32 v207, v209
	v_pk_add_f32 v[148:149], v[148:149], v[206:207]
	ds_bpermute_b32 v181, v165, v162
	v_add_f32_e32 v148, v148, v149
	ds_bpermute_b32 v155, v165, v158
	ds_bpermute_b32 v182, v210, v159
	ds_bpermute_b32 v149, v165, v148
	s_waitcnt lgkmcnt(3)
	v_add_f32_e32 v162, v162, v181
	ds_bpermute_b32 v181, v210, v162
	s_waitcnt lgkmcnt(3)
	v_add_f32_e32 v158, v158, v155
	s_waitcnt lgkmcnt(2)
	v_add_f32_e32 v159, v159, v182
	s_waitcnt lgkmcnt(1)
	v_add_f32_e32 v149, v148, v149
	ds_bpermute_b32 v165, v210, v158
	v_fmamk_f32 v155, v159, 0x3a800000, v177
	ds_bpermute_b32 v159, v210, v149
	s_waitcnt lgkmcnt(2)
	v_add_f32_e32 v162, v162, v181
	v_fmamk_f32 v163, v163, 0x3a800000, v177
	s_waitcnt lgkmcnt(1)
	v_add_f32_e32 v148, v158, v165
	v_fmamk_f32 v179, v162, 0x3a800000, v177
	s_waitcnt lgkmcnt(0)
	v_add_f32_e32 v149, v149, v159
	v_fmamk_f32 v148, v148, 0x3a800000, v177
	v_fmamk_f32 v149, v149, 0x3a800000, v177
	v_rsq_f32_e32 v167, v163
	v_rsq_f32_e32 v162, v178
	v_rsq_f32_e32 v163, v179
	v_rsq_f32_e32 v155, v155
	v_rsq_f32_e32 v148, v148
	v_rsq_f32_e32 v149, v149
	v_mov_b64_e32 v[158:159], v[146:147]

.Lzskip_7:
	s_and_b64 vcc, exec, s[50:51]
	s_cbranch_vccz .LBB0_1608
.LBB0_1608:
	v_lshl_or_b32 v204, s44, 8, v244
	v_lshl_add_u32 v234, s54, 8, v242
	v_ashrrev_i32_e32 v205, 31, v204
	v_lshlrev_b64 v[236:237], 1, v[204:205]
	v_ashrrev_i32_e32 v235, 31, v234
	v_lshl_add_u64 v[124:125], s[12:13], 0, v[236:237]
	v_lshlrev_b64 v[238:239], 11, v[234:235]
	v_lshl_add_u64 v[120:121], v[124:125], 0, v[238:239]
	global_load_dwordx4 v[188:191], v[120:121], off
	global_load_dwordx4 v[184:187], v[120:121], off offset:256
	v_or_b32_e32 v230, 16, v234
	v_ashrrev_i32_e32 v231, 31, v230
	v_or_b32_e32 v226, 32, v234
	v_lshlrev_b64 v[232:233], 11, v[230:231]
	v_ashrrev_i32_e32 v227, 31, v226
	v_or_b32_e32 v222, 48, v234
	v_lshl_add_u64 v[120:121], v[124:125], 0, v[232:233]
	v_lshlrev_b64 v[228:229], 11, v[226:227]
	v_ashrrev_i32_e32 v223, 31, v222
	v_add_u32_e32 v218, 0x80, v234
	global_load_dwordx4 v[180:183], v[120:121], off
	global_load_dwordx4 v[176:179], v[120:121], off offset:256
	v_lshl_add_u64 v[120:121], v[124:125], 0, v[228:229]
	v_lshlrev_b64 v[224:225], 11, v[222:223]
	v_ashrrev_i32_e32 v219, 31, v218
	v_add_u32_e32 v214, 0x90, v234
	global_load_dwordx4 v[172:175], v[120:121], off
	global_load_dwordx4 v[168:171], v[120:121], off offset:256
	v_lshl_add_u64 v[120:121], v[124:125], 0, v[224:225]
	v_lshlrev_b64 v[220:221], 11, v[218:219]
	v_ashrrev_i32_e32 v215, 31, v214
	v_add_u32_e32 v210, 0xa0, v234
	v_add_u32_e32 v206, 0xb0, v234
	global_load_dwordx4 v[164:167], v[120:121], off
	global_load_dwordx4 v[160:163], v[120:121], off offset:256
	v_lshl_add_u64 v[120:121], v[124:125], 0, v[220:221]
	v_lshlrev_b64 v[216:217], 11, v[214:215]
	v_ashrrev_i32_e32 v211, 31, v210
	v_ashrrev_i32_e32 v207, 31, v206
	global_load_dwordx4 v[156:159], v[120:121], off
	global_load_dwordx4 v[152:155], v[120:121], off offset:256
	v_lshl_add_u64 v[120:121], v[124:125], 0, v[216:217]
	v_lshlrev_b64 v[212:213], 11, v[210:211]
	v_lshlrev_b64 v[208:209], 11, v[206:207]
	global_load_dwordx4 v[148:151], v[120:121], off
	global_load_dwordx4 v[144:147], v[120:121], off offset:256
	v_lshl_add_u64 v[120:121], v[124:125], 0, v[212:213]
	v_lshl_add_u64 v[124:125], v[124:125], 0, v[208:209]
	global_load_dwordx4 v[128:131], v[120:121], off
	s_nop 0
	global_load_dwordx4 v[120:123], v[120:121], off offset:256
	s_nop 0
	global_load_dwordx4 v[132:135], v[124:125], off
	s_nop 0
	global_load_dwordx4 v[124:127], v[124:125], off offset:256
	v_lshl_add_u64 v[238:239], s[12:13], 0, v[238:239]
	v_lshl_add_u64 v[236:237], v[238:239], 0, v[236:237]
	s_lshl_b32 s76, s44, 2
	s_ashr_i32 s77, s76, 31
	s_waitcnt vmcnt(0)
	v_lshlrev_b32_e32 v250, 16, v188
	v_and_b32_e32 v251, 0xffff0000, v188
	v_lshlrev_b32_e32 v188, 16, v189
	v_and_b32_e32 v189, 0xffff0000, v189
	v_lshlrev_b32_e32 v252, 16, v190
	v_and_b32_e32 v253, 0xffff0000, v190
	v_lshlrev_b32_e32 v190, 16, v191
	v_and_b32_e32 v191, 0xffff0000, v191
	v_pk_fma_f32 v[142:143], v[142:143], 0.5, v[188:189] op_sel_hi:[1,0,1]
	v_pk_fma_f32 v[140:141], v[140:141], 0.5, v[250:251] op_sel_hi:[1,0,1]
	v_pk_fma_f32 v[188:189], v[138:139], 0.5, v[190:191] op_sel_hi:[1,0,1]
	v_pk_fma_f32 v[190:191], v[136:137], 0.5, v[252:253] op_sel_hi:[1,0,1]
	v_cvt_pk_bf16_f32 v136, v140, v141
	v_cvt_pk_bf16_f32 v137, v142, v143
	s_nop 0
	v_cvt_pk_bf16_f32 v138, v190, v191
	v_cvt_pk_bf16_f32 v139, v188, v189
	global_store_dwordx4 v[236:237], v[136:139], off
	s_nop 1
	v_pk_fma_f32 v[136:137], v[140:141], v[140:141], 0 op_sel_hi:[1,1,0]
	v_pk_fma_f32 v[138:139], v[142:143], v[142:143], 0 op_sel_hi:[1,1,0]
	v_lshlrev_b32_e32 v140, 16, v184
	v_and_b32_e32 v141, 0xffff0000, v184
	v_lshlrev_b32_e32 v142, 16, v185
	v_and_b32_e32 v143, 0xffff0000, v185
	v_lshlrev_b32_e32 v184, 16, v186
	v_and_b32_e32 v185, 0xffff0000, v186
	v_lshlrev_b32_e32 v186, 16, v187
	v_and_b32_e32 v187, 0xffff0000, v187
	v_pk_fma_f32 v[138:139], v[188:189], v[188:189], v[138:139]
	v_pk_fma_f32 v[136:137], v[190:191], v[190:191], v[136:137]
	v_pk_fma_f32 v[118:119], v[118:119], 0.5, v[142:143] op_sel_hi:[1,0,1]
	v_pk_fma_f32 v[116:117], v[116:117], 0.5, v[140:141] op_sel_hi:[1,0,1]
	v_pk_fma_f32 v[140:141], v[114:115], 0.5, v[186:187] op_sel_hi:[1,0,1]
	v_pk_fma_f32 v[142:143], v[112:113], 0.5, v[184:185] op_sel_hi:[1,0,1]
	v_cvt_pk_bf16_f32 v112, v116, v117
	v_cvt_pk_bf16_f32 v113, v118, v119
	s_nop 0
	v_cvt_pk_bf16_f32 v114, v142, v143
	v_cvt_pk_bf16_f32 v115, v140, v141
	global_store_dwordx4 v[236:237], v[112:115], off offset:256
	s_nop 1
	v_pk_fma_f32 v[112:113], v[116:117], v[116:117], v[136:137]
	v_pk_fma_f32 v[114:115], v[118:119], v[118:119], v[138:139]
	v_pk_fma_f32 v[112:113], v[142:143], v[142:143], v[112:113]
	v_pk_fma_f32 v[114:115], v[140:141], v[140:141], v[114:115]
	v_add_f32_e32 v112, v112, v113
	v_add_f32_e32 v113, v114, v115
	v_and_b32_e32 v114, 64, v248
	v_add_f32_e32 v113, v112, v113
	v_xor_b32_e32 v112, 16, v248
	v_add_u32_e32 v115, 64, v114
	v_cmp_lt_i32_e32 vcc, v112, v115
	s_nop 1
	v_cndmask_b32_e32 v112, v248, v112, vcc
	v_lshlrev_b32_e32 v112, 2, v112
	v_mov_b32_e32 v114, v113
	s_nop 1
	v_permlane16_swap_b32 v114, v113
	s_waitcnt lgkmcnt(0)
	v_add_f32_e32 v114, v113, v114
	v_xor_b32_e32 v113, 32, v248
	v_cmp_lt_i32_e32 vcc, v113, v115
	s_nop 1
	v_cndmask_b32_e32 v113, v248, v113, vcc
	v_lshlrev_b32_e32 v113, 2, v113
	v_mov_b32_e32 v115, v114
	s_nop 1
	v_permlane32_swap_b32 v115, v114
	s_and_saveexec_b64 s[54:55], s[4:5]
	s_cbranch_execz .LBB0_1610
	v_lshlrev_b64 v[116:117], 6, v[234:235]
	v_lshl_add_u64 v[116:117], s[70:71], 0, v[116:117]
	v_lshl_add_u64 v[116:117], s[76:77], 2, v[116:117]
	s_lshl_b32 s44, s20, 2
	v_lshl_add_u64 v[116:117], v[116:117], 0, s[44:45]
	s_waitcnt lgkmcnt(0)
	v_add_f32_e32 v114, v114, v115
	global_store_dword v[116:117], v114, off

.Lzskip_8:
	s_and_b64 vcc, exec, s[44:45]
	s_cbranch_vccz .LBB0_1763
.LBB0_1763:
	v_lshl_add_u32 v166, s76, 8, v176
	v_or_b32_e32 v164, 16, v166
	v_or_b32_e32 v162, 32, v166
	v_or_b32_e32 v160, 48, v166
	s_mov_b64 s[54:55], -1
	s_cmp_gt_u32 s59, 13
	v_ashrrev_i32_e32 v167, 31, v166
	v_ashrrev_i32_e32 v165, 31, v164
	v_ashrrev_i32_e32 v163, 31, v162
	v_ashrrev_i32_e32 v161, 31, v160
	s_cbranch_scc1 .LBB0_1768
	s_andn2_b64 vcc, exec, s[54:55]
	s_cbranch_vccz .LBB0_1769

.LBB0_1772:
	s_andn2_b64 vcc, exec, s[8:9]
	s_cbranch_vccnz .LBB0_1755
	s_branch .LBB0_1755

.Lzskip_9:
	s_and_b64 vcc, exec, s[48:49]
	s_cbranch_vccz .LBB0_2040
.LBB0_2040:
	v_lshl_or_b32 v204, s10, 8, v244
	v_lshl_add_u32 v234, s74, 8, v242
	v_ashrrev_i32_e32 v205, 31, v204
	v_lshlrev_b64 v[236:237], 1, v[204:205]
	v_ashrrev_i32_e32 v235, 31, v234
	v_lshl_add_u64 v[124:125], s[12:13], 0, v[236:237]
	v_lshlrev_b64 v[238:239], 11, v[234:235]
	v_lshl_add_u64 v[120:121], v[124:125], 0, v[238:239]
	global_load_dwordx4 v[188:191], v[120:121], off
	global_load_dwordx4 v[184:187], v[120:121], off offset:256
	v_or_b32_e32 v230, 16, v234
	v_ashrrev_i32_e32 v231, 31, v230
	v_or_b32_e32 v226, 32, v234
	v_lshlrev_b64 v[232:233], 11, v[230:231]
	v_ashrrev_i32_e32 v227, 31, v226
	v_or_b32_e32 v222, 48, v234
	v_lshl_add_u64 v[120:121], v[124:125], 0, v[232:233]
	v_lshlrev_b64 v[228:229], 11, v[226:227]
	v_ashrrev_i32_e32 v223, 31, v222
	v_add_u32_e32 v218, 0x80, v234
	global_load_dwordx4 v[180:183], v[120:121], off
	global_load_dwordx4 v[176:179], v[120:121], off offset:256
	v_lshl_add_u64 v[120:121], v[124:125], 0, v[228:229]
	v_lshlrev_b64 v[224:225], 11, v[222:223]
	v_ashrrev_i32_e32 v219, 31, v218
	v_add_u32_e32 v214, 0x90, v234
	global_load_dwordx4 v[172:175], v[120:121], off
	global_load_dwordx4 v[168:171], v[120:121], off offset:256
	v_lshl_add_u64 v[120:121], v[124:125], 0, v[224:225]
	v_lshlrev_b64 v[220:221], 11, v[218:219]
	v_ashrrev_i32_e32 v215, 31, v214
	v_add_u32_e32 v210, 0xa0, v234
	v_add_u32_e32 v206, 0xb0, v234
	global_load_dwordx4 v[164:167], v[120:121], off
	global_load_dwordx4 v[160:163], v[120:121], off offset:256
	v_lshl_add_u64 v[120:121], v[124:125], 0, v[220:221]
	v_lshlrev_b64 v[216:217], 11, v[214:215]
	v_ashrrev_i32_e32 v211, 31, v210
	v_ashrrev_i32_e32 v207, 31, v206
	global_load_dwordx4 v[156:159], v[120:121], off
	global_load_dwordx4 v[152:155], v[120:121], off offset:256
	v_lshl_add_u64 v[120:121], v[124:125], 0, v[216:217]
	v_lshlrev_b64 v[212:213], 11, v[210:211]
	v_lshlrev_b64 v[208:209], 11, v[206:207]
	global_load_dwordx4 v[148:151], v[120:121], off
	global_load_dwordx4 v[144:147], v[120:121], off offset:256
	v_lshl_add_u64 v[120:121], v[124:125], 0, v[212:213]
	v_lshl_add_u64 v[124:125], v[124:125], 0, v[208:209]
	global_load_dwordx4 v[128:131], v[120:121], off
	s_nop 0
	global_load_dwordx4 v[120:123], v[120:121], off offset:256
	s_nop 0
	global_load_dwordx4 v[132:135], v[124:125], off
	s_nop 0
	global_load_dwordx4 v[124:127], v[124:125], off offset:256
	v_lshl_add_u64 v[238:239], s[12:13], 0, v[238:239]
	v_lshl_add_u64 v[236:237], v[238:239], 0, v[236:237]
	s_lshl_b32 s74, s10, 2
	s_ashr_i32 s75, s74, 31
	s_waitcnt vmcnt(0)
	v_lshlrev_b32_e32 v250, 16, v188
	v_and_b32_e32 v251, 0xffff0000, v188
	v_lshlrev_b32_e32 v188, 16, v189
	v_and_b32_e32 v189, 0xffff0000, v189
	v_lshlrev_b32_e32 v252, 16, v190
	v_and_b32_e32 v253, 0xffff0000, v190
	v_lshlrev_b32_e32 v190, 16, v191
	v_and_b32_e32 v191, 0xffff0000, v191
	v_pk_add_f32 v[142:143], v[142:143], v[188:189]
	v_pk_add_f32 v[140:141], v[140:141], v[250:251]
	v_pk_add_f32 v[188:189], v[138:139], v[190:191]
	v_pk_add_f32 v[190:191], v[136:137], v[252:253]
	v_cvt_pk_bf16_f32 v136, v140, v141
	v_cvt_pk_bf16_f32 v137, v142, v143
	s_nop 0
	v_cvt_pk_bf16_f32 v138, v190, v191
	v_cvt_pk_bf16_f32 v139, v188, v189
	global_store_dwordx4 v[236:237], v[136:139], off
	s_nop 1
	v_pk_fma_f32 v[136:137], v[140:141], v[140:141], 0 op_sel_hi:[1,1,0]
	v_pk_fma_f32 v[138:139], v[142:143], v[142:143], 0 op_sel_hi:[1,1,0]
	v_lshlrev_b32_e32 v140, 16, v184
	v_and_b32_e32 v141, 0xffff0000, v184
	v_lshlrev_b32_e32 v142, 16, v185
	v_and_b32_e32 v143, 0xffff0000, v185
	v_lshlrev_b32_e32 v184, 16, v186
	v_and_b32_e32 v185, 0xffff0000, v186
	v_lshlrev_b32_e32 v186, 16, v187
	v_and_b32_e32 v187, 0xffff0000, v187
	v_pk_fma_f32 v[138:139], v[188:189], v[188:189], v[138:139]
	v_pk_fma_f32 v[136:137], v[190:191], v[190:191], v[136:137]
	v_pk_add_f32 v[118:119], v[118:119], v[142:143]
	v_pk_add_f32 v[116:117], v[116:117], v[140:141]
	v_pk_add_f32 v[140:141], v[114:115], v[186:187]
	v_pk_add_f32 v[142:143], v[112:113], v[184:185]
	v_cvt_pk_bf16_f32 v112, v116, v117
	v_cvt_pk_bf16_f32 v113, v118, v119
	s_nop 0
	v_cvt_pk_bf16_f32 v114, v142, v143
	v_cvt_pk_bf16_f32 v115, v140, v141
	global_store_dwordx4 v[236:237], v[112:115], off offset:256
	s_nop 1
	v_pk_fma_f32 v[112:113], v[116:117], v[116:117], v[136:137]
	v_pk_fma_f32 v[114:115], v[118:119], v[118:119], v[138:139]
	v_pk_fma_f32 v[112:113], v[142:143], v[142:143], v[112:113]
	v_pk_fma_f32 v[114:115], v[140:141], v[140:141], v[114:115]
	v_add_f32_e32 v112, v112, v113
	v_add_f32_e32 v113, v114, v115
	v_and_b32_e32 v114, 64, v248
	v_add_f32_e32 v113, v112, v113
	v_xor_b32_e32 v112, 16, v248
	v_add_u32_e32 v115, 64, v114
	v_cmp_lt_i32_e32 vcc, v112, v115
	s_nop 1
	v_cndmask_b32_e32 v112, v248, v112, vcc
	v_lshlrev_b32_e32 v112, 2, v112
	v_mov_b32_e32 v114, v113
	s_nop 1
	v_permlane16_swap_b32 v114, v113
	s_waitcnt lgkmcnt(0)
	v_add_f32_e32 v114, v113, v114
	v_xor_b32_e32 v113, 32, v248
	v_cmp_lt_i32_e32 vcc, v113, v115
	s_nop 1
	v_cndmask_b32_e32 v113, v248, v113, vcc
	v_lshlrev_b32_e32 v113, 2, v113
	v_mov_b32_e32 v115, v114
	s_nop 1
	v_permlane32_swap_b32 v115, v114
	s_and_saveexec_b64 s[54:55], s[4:5]
	s_cbranch_execz .LBB0_2042
	v_lshlrev_b64 v[116:117], 6, v[234:235]
	v_lshl_add_u64 v[116:117], s[70:71], 0, v[116:117]
	v_lshl_add_u64 v[116:117], s[74:75], 2, v[116:117]
	s_lshl_b32 s10, s20, 2
	v_lshl_add_u64 v[116:117], v[116:117], 0, s[10:11]
	s_waitcnt lgkmcnt(0)
	v_add_f32_e32 v114, v114, v115
	global_store_dword v[116:117], v114, off

.Lzskip_10:
	s_and_b64 vcc, exec, s[42:43]
	s_cbranch_vccz .LBB0_2195
.LBB0_2195:
	v_lshl_add_u32 v160, s52, 8, v170
	v_or_b32_e32 v156, 16, v160
	v_or_b32_e32 v152, 32, v160
	v_or_b32_e32 v150, 48, v160
	s_mov_b64 s[52:53], -1
	s_cmp_gt_u32 s57, 13
	v_ashrrev_i32_e32 v161, 31, v160
	v_ashrrev_i32_e32 v157, 31, v156
	v_ashrrev_i32_e32 v153, 31, v152
	v_ashrrev_i32_e32 v151, 31, v150
	v_add_u32_e32 v164, 0x80, v160
	s_cbranch_scc0 .LBB0_2197
	v_lshlrev_b64 v[146:147], 6, v[160:161]
	v_lshlrev_b64 v[148:149], 6, v[156:157]
	v_lshl_add_u64 v[146:147], v[138:139], 0, v[146:147]
	v_lshl_add_u64 v[148:149], v[138:139], 0, v[148:149]
	global_load_dwordx4 v[178:181], v[146:147], off
	global_load_dwordx4 v[182:185], v[148:149], off
	v_lshlrev_b64 v[148:149], 6, v[152:153]
	v_lshl_add_u64 v[148:149], v[138:139], 0, v[148:149]
	global_load_dwordx4 v[186:189], v[148:149], off
	v_lshlrev_b64 v[148:149], 6, v[150:151]
	v_lshl_add_u64 v[148:149], v[138:139], 0, v[148:149]
	global_load_dwordx4 v[190:193], v[148:149], off
	v_add_co_u32_e32 v148, vcc, s33, v146
	v_add_u32_e32 v146, 0x80, v160
	s_nop 0
	v_addc_co_u32_e32 v149, vcc, 0, v147, vcc
	v_ashrrev_i32_e32 v147, 31, v146
	v_lshlrev_b64 v[154:155], 6, v[146:147]
	v_lshl_add_u64 v[154:155], v[138:139], 0, v[154:155]
	global_load_dwordx4 v[194:197], v[148:149], off offset:2048
	global_load_dwordx4 v[198:201], v[154:155], off
	global_load_dwordx4 v[202:205], v[148:149], off offset:1024
	global_load_dwordx4 v[206:209], v[148:149], off offset:3072
	v_xor_b32_e32 v148, 16, v168
	v_xor_b32_e32 v149, 32, v168
	v_cmp_lt_i32_e32 vcc, v148, v169
	s_mov_b64 s[52:53], 0
	s_waitcnt vmcnt(0)
	v_mov_b32_e32 v154, v183
	v_cndmask_b32_e32 v148, v168, v148, vcc
	v_cmp_lt_i32_e32 vcc, v149, v169
	v_lshlrev_b32_e32 v165, 2, v148
	v_mov_b32_e32 v148, v179
	v_cndmask_b32_e32 v149, v168, v149, vcc
	v_lshlrev_b32_e32 v210, 2, v149
	v_mov_b32_e32 v149, v180
	v_mov_b32_e32 v179, v181
	v_mov_b32_e32 v155, v184
	v_mov_b32_e32 v183, v185
	v_pk_add_f32 v[148:149], v[148:149], v[178:179]
	v_pk_add_f32 v[154:155], v[154:155], v[182:183]
	v_add_f32_e32 v178, v148, v149
	v_mov_b32_e32 v148, v199
	v_mov_b32_e32 v149, v200
	v_mov_b32_e32 v199, v201
	v_mov_b32_e32 v158, v187
	v_mov_b32_e32 v159, v188
	v_mov_b32_e32 v187, v189
	v_mov_b32_e32 v162, v191
	v_mov_b32_e32 v163, v192
	v_mov_b32_e32 v191, v193
	v_add_f32_e32 v179, v154, v155
	v_mov_b32_e32 v154, v203
	v_mov_b32_e32 v155, v204
	v_mov_b32_e32 v203, v205
	v_pk_add_f32 v[148:149], v[148:149], v[198:199]
	v_pk_add_f32 v[158:159], v[158:159], v[186:187]
	v_pk_add_f32 v[162:163], v[162:163], v[190:191]
	v_mov_b32_e32 v166, v195
	v_mov_b32_e32 v167, v196
	v_mov_b32_e32 v195, v197
	v_pk_add_f32 v[154:155], v[154:155], v[202:203]
	v_add_f32_e32 v148, v148, v149
	v_add_f32_e32 v180, v158, v159
	v_add_f32_e32 v162, v162, v163
	v_pk_add_f32 v[158:159], v[166:167], v[194:195]
	ds_bpermute_b32 v163, v165, v178
	v_add_f32_e32 v149, v154, v155
	ds_bpermute_b32 v154, v165, v148
	ds_bpermute_b32 v166, v165, v179
	ds_bpermute_b32 v167, v165, v180
	v_add_f32_e32 v158, v158, v159
	ds_bpermute_b32 v159, v165, v149
	s_waitcnt lgkmcnt(4)
	v_add_f32_e32 v163, v178, v163
	s_waitcnt lgkmcnt(3)
	v_add_f32_e32 v148, v148, v154
	s_waitcnt lgkmcnt(2)
	v_add_f32_e32 v166, v179, v166
	s_waitcnt lgkmcnt(1)
	v_add_f32_e32 v167, v180, v167
	ds_bpermute_b32 v178, v210, v163
	s_waitcnt lgkmcnt(1)
	v_add_f32_e32 v159, v149, v159
	ds_bpermute_b32 v149, v210, v148
	ds_bpermute_b32 v179, v210, v166
	ds_bpermute_b32 v180, v210, v167
	s_waitcnt lgkmcnt(3)
	v_add_f32_e32 v154, v163, v178
	v_fmamk_f32 v154, v154, 0x3a800000, v177
	s_waitcnt lgkmcnt(2)
	v_add_f32_e32 v148, v148, v149
	s_waitcnt lgkmcnt(1)
	v_add_f32_e32 v163, v166, v179
	s_waitcnt lgkmcnt(0)
	v_add_f32_e32 v166, v167, v180
	v_fmamk_f32 v148, v148, 0x3a800000, v177
	v_fmamk_f32 v178, v166, 0x3a800000, v177
	v_rsq_f32_e32 v166, v154
	v_rsq_f32_e32 v154, v148
	v_mov_b32_e32 v148, v207
	v_mov_b32_e32 v149, v208
	v_mov_b32_e32 v207, v209
	v_pk_add_f32 v[148:149], v[148:149], v[206:207]
	ds_bpermute_b32 v181, v165, v162
	v_add_f32_e32 v148, v148, v149
	ds_bpermute_b32 v155, v165, v158
	ds_bpermute_b32 v182, v210, v159
	ds_bpermute_b32 v149, v165, v148
	s_waitcnt lgkmcnt(3)
	v_add_f32_e32 v162, v162, v181
	ds_bpermute_b32 v181, v210, v162
	s_waitcnt lgkmcnt(3)
	v_add_f32_e32 v158, v158, v155
	s_waitcnt lgkmcnt(2)
	v_add_f32_e32 v159, v159, v182
	s_waitcnt lgkmcnt(1)
	v_add_f32_e32 v149, v148, v149
	ds_bpermute_b32 v165, v210, v158
	v_fmamk_f32 v155, v159, 0x3a800000, v177
	ds_bpermute_b32 v159, v210, v149
	s_waitcnt lgkmcnt(2)
	v_add_f32_e32 v162, v162, v181
	v_fmamk_f32 v163, v163, 0x3a800000, v177
	s_waitcnt lgkmcnt(1)
	v_add_f32_e32 v148, v158, v165
	v_fmamk_f32 v179, v162, 0x3a800000, v177
	s_waitcnt lgkmcnt(0)
	v_add_f32_e32 v149, v149, v159
	v_fmamk_f32 v148, v148, 0x3a800000, v177
	v_fmamk_f32 v149, v149, 0x3a800000, v177
	v_rsq_f32_e32 v167, v163
	v_rsq_f32_e32 v162, v178
	v_rsq_f32_e32 v163, v179
	v_rsq_f32_e32 v155, v155
	v_rsq_f32_e32 v148, v148
	v_rsq_f32_e32 v149, v149
	v_mov_b64_e32 v[158:159], v[146:147]

.LBB0_2199:
	s_waitcnt lgkmcnt(0)
	v_mul_f32_e32 v164, 0xbfb8aa3b, v166
	v_mul_f32_e32 v147, v166, v166
	v_pk_mul_f32 v[178:179], v[126:127], v[164:165] op_sel_hi:[1,0]
	v_pk_mul_f32 v[122:123], v[126:127], v[122:123]
	v_pk_mul_f32 v[126:127], v[116:117], v[164:165] op_sel_hi:[1,0]
	v_rcp_f32_e32 v166, v147
	v_pk_mul_f32 v[180:181], v[124:125], v[164:165] op_sel_hi:[1,0]
	v_exp_f32_e32 v126, v126
	v_exp_f32_e32 v127, v127
	v_exp_f32_e32 v180, v180
	v_exp_f32_e32 v178, v178
	v_exp_f32_e32 v179, v179
	v_exp_f32_e32 v181, v181
	v_pk_mul_f32 v[120:121], v[124:125], v[120:121]
	v_pk_mul_f32 v[124:125], v[118:119], v[164:165] op_sel_hi:[1,0]
	v_pk_fma_f32 v[126:127], v[126:127], v[166:167], v[166:167] op_sel_hi:[1,0,0]
	v_exp_f32_e32 v124, v124
	v_exp_f32_e32 v125, v125
	v_pk_fma_f32 v[178:179], v[178:179], v[166:167], v[166:167] op_sel_hi:[1,0,0]
	v_pk_fma_f32 v[180:181], v[180:181], v[166:167], v[166:167] op_sel_hi:[1,0,0]
	v_rcp_f32_e32 v126, v126
	v_rcp_f32_e32 v127, v127
	v_rcp_f32_e32 v180, v180
	v_rcp_f32_e32 v181, v181
	v_rcp_f32_e32 v178, v178
	v_rcp_f32_e32 v179, v179
	v_pk_fma_f32 v[124:125], v[124:125], v[166:167], v[166:167] op_sel_hi:[1,0,0]
	v_pk_mul_f32 v[112:113], v[116:117], v[112:113]
	v_rcp_f32_e32 v124, v124
	v_rcp_f32_e32 v125, v125
	v_pk_mul_f32 v[112:113], v[112:113], v[126:127]
	v_pk_mul_f32 v[122:123], v[122:123], v[178:179]
	v_pk_mul_f32 v[120:121], v[120:121], v[180:181]
	v_pk_mul_f32 v[114:115], v[118:119], v[114:115]
	v_cvt_pk_bf16_f32 v116, v120, v121
	v_cvt_pk_bf16_f32 v117, v122, v123
	v_cvt_pk_bf16_f32 v118, v112, v113
	v_mov_b64_e32 v[112:113], s[64:65]
	v_pk_mul_f32 v[114:115], v[114:115], v[124:125]
	v_mad_u64_u32 v[120:121], s[52:53], v160, s54, v[112:113]
	v_cvt_pk_bf16_f32 v119, v114, v115
	v_mov_b32_e32 v114, v121
	v_mul_f32_e32 v122, 0xbfb8aa3b, v167
	v_mul_f32_e32 v123, v167, v167
	v_mad_u64_u32 v[114:115], s[52:53], v161, s54, v[114:115]
	v_pk_mul_f32 v[126:127], v[110:111], v[122:123] op_sel_hi:[1,0]
	v_pk_mul_f32 v[160:161], v[108:109], v[122:123] op_sel_hi:[1,0]
	v_pk_mul_f32 v[106:107], v[110:111], v[106:107]
	v_pk_mul_f32 v[104:105], v[108:109], v[104:105]
	v_pk_mul_f32 v[108:109], v[102:103], v[122:123] op_sel_hi:[1,0]
	v_pk_mul_f32 v[110:111], v[100:101], v[122:123] op_sel_hi:[1,0]
	v_rcp_f32_e32 v124, v123
	v_exp_f32_e32 v110, v110
	v_exp_f32_e32 v108, v108
	v_exp_f32_e32 v109, v109
	v_exp_f32_e32 v111, v111
	v_lshl_or_b32 v182, s56, 7, v173
	v_exp_f32_e32 v160, v160
	v_exp_f32_e32 v126, v126
	v_exp_f32_e32 v127, v127
	v_exp_f32_e32 v161, v161
	v_ashrrev_i32_e32 v183, 31, v182
	v_mov_b32_e32 v121, v114
	v_lshlrev_b64 v[114:115], 1, v[182:183]
	v_lshl_add_u64 v[120:121], v[120:121], 0, v[114:115]
	v_pk_fma_f32 v[108:109], v[108:109], v[124:125], v[124:125] op_sel_hi:[1,0,0]
	v_pk_fma_f32 v[110:111], v[110:111], v[124:125], v[124:125] op_sel_hi:[1,0,0]
	global_store_dwordx4 v[120:121], v[116:119], off
	v_rcp_f32_e32 v110, v110
	v_rcp_f32_e32 v108, v108
	v_pk_fma_f32 v[116:117], v[126:127], v[124:125], v[124:125] op_sel_hi:[1,0,0]
	v_pk_fma_f32 v[118:119], v[160:161], v[124:125], v[124:125] op_sel_hi:[1,0,0]
	v_rcp_f32_e32 v109, v109
	v_rcp_f32_e32 v111, v111
	v_rcp_f32_e32 v118, v118
	v_rcp_f32_e32 v119, v119
	v_rcp_f32_e32 v116, v116
	v_rcp_f32_e32 v117, v117
	v_pk_mul_f32 v[98:99], v[102:103], v[98:99]
	v_pk_mul_f32 v[96:97], v[100:101], v[96:97]
	v_pk_mul_f32 v[100:101], v[98:99], v[108:109]
	v_pk_mul_f32 v[98:99], v[96:97], v[110:111]
	v_pk_mul_f32 v[106:107], v[106:107], v[116:117]
	v_pk_mul_f32 v[104:105], v[104:105], v[118:119]
	v_pk_mul_f32 v[90:91], v[94:95], v[90:91]
	v_cvt_pk_bf16_f32 v96, v104, v105
	v_cvt_pk_bf16_f32 v97, v106, v107
	v_cvt_pk_bf16_f32 v98, v98, v99
	v_cvt_pk_bf16_f32 v99, v100, v101
	v_mad_u64_u32 v[100:101], s[52:53], v156, s54, v[112:113]
	v_mul_f32_e32 v102, 0xbfb8aa3b, v162
	v_mul_f32_e32 v103, v162, v162
	v_pk_mul_f32 v[106:107], v[94:95], v[102:103] op_sel_hi:[1,0]
	v_pk_mul_f32 v[108:109], v[92:93], v[102:103] op_sel_hi:[1,0]
	v_pk_mul_f32 v[88:89], v[92:93], v[88:89]
	v_pk_mul_f32 v[92:93], v[86:87], v[102:103] op_sel_hi:[1,0]
	v_pk_mul_f32 v[94:95], v[84:85], v[102:103] op_sel_hi:[1,0]
	v_rcp_f32_e32 v104, v103
	v_exp_f32_e32 v94, v94
	v_exp_f32_e32 v92, v92
	v_exp_f32_e32 v93, v93
	v_exp_f32_e32 v95, v95
	v_exp_f32_e32 v108, v108
	v_exp_f32_e32 v106, v106
	v_exp_f32_e32 v107, v107
	v_exp_f32_e32 v109, v109
	v_lshl_add_u64 v[100:101], v[100:101], 0, v[114:115]
	v_pk_fma_f32 v[92:93], v[92:93], v[104:105], v[104:105] op_sel_hi:[1,0,0]
	v_pk_fma_f32 v[94:95], v[94:95], v[104:105], v[104:105] op_sel_hi:[1,0,0]
	global_store_dwordx4 v[100:101], v[96:99], off
	v_rcp_f32_e32 v94, v94
	v_rcp_f32_e32 v92, v92
	v_pk_fma_f32 v[96:97], v[106:107], v[104:105], v[104:105] op_sel_hi:[1,0,0]
	v_pk_fma_f32 v[98:99], v[108:109], v[104:105], v[104:105] op_sel_hi:[1,0,0]
	v_rcp_f32_e32 v93, v93
	v_rcp_f32_e32 v95, v95
	v_rcp_f32_e32 v98, v98
	v_rcp_f32_e32 v99, v99
	v_rcp_f32_e32 v96, v96
	v_rcp_f32_e32 v97, v97
	v_pk_mul_f32 v[82:83], v[86:87], v[82:83]
	v_pk_mul_f32 v[80:81], v[84:85], v[80:81]
	v_pk_mul_f32 v[84:85], v[82:83], v[92:93]
	v_pk_mul_f32 v[82:83], v[80:81], v[94:95]
	v_pk_mul_f32 v[90:91], v[90:91], v[96:97]
	v_pk_mul_f32 v[88:89], v[88:89], v[98:99]
	v_pk_mul_f32 v[74:75], v[78:79], v[74:75]
	v_cvt_pk_bf16_f32 v80, v88, v89
	v_cvt_pk_bf16_f32 v81, v90, v91
	v_cvt_pk_bf16_f32 v82, v82, v83
	v_cvt_pk_bf16_f32 v83, v84, v85
	v_mad_u64_u32 v[84:85], s[52:53], v152, s54, v[112:113]
	v_mul_f32_e32 v86, 0xbfb8aa3b, v163
	v_mul_f32_e32 v87, v163, v163
	v_pk_mul_f32 v[90:91], v[78:79], v[86:87] op_sel_hi:[1,0]
	v_pk_mul_f32 v[92:93], v[76:77], v[86:87] op_sel_hi:[1,0]
	v_pk_mul_f32 v[72:73], v[76:77], v[72:73]
	v_pk_mul_f32 v[76:77], v[70:71], v[86:87] op_sel_hi:[1,0]
	v_pk_mul_f32 v[78:79], v[68:69], v[86:87] op_sel_hi:[1,0]
	v_rcp_f32_e32 v88, v87
	v_exp_f32_e32 v78, v78
	v_exp_f32_e32 v76, v76
	v_exp_f32_e32 v77, v77
	v_exp_f32_e32 v79, v79
	v_exp_f32_e32 v92, v92
	v_exp_f32_e32 v90, v90
	v_exp_f32_e32 v91, v91
	v_exp_f32_e32 v93, v93
	v_lshl_add_u64 v[84:85], v[84:85], 0, v[114:115]
	v_pk_fma_f32 v[76:77], v[76:77], v[88:89], v[88:89] op_sel_hi:[1,0,0]
	v_pk_fma_f32 v[78:79], v[78:79], v[88:89], v[88:89] op_sel_hi:[1,0,0]
	global_store_dwordx4 v[84:85], v[80:83], off
	v_rcp_f32_e32 v78, v78
	v_rcp_f32_e32 v76, v76
	v_pk_fma_f32 v[80:81], v[90:91], v[88:89], v[88:89] op_sel_hi:[1,0,0]
	v_pk_fma_f32 v[82:83], v[92:93], v[88:89], v[88:89] op_sel_hi:[1,0,0]
	v_rcp_f32_e32 v77, v77
	v_rcp_f32_e32 v79, v79
	v_rcp_f32_e32 v82, v82
	v_rcp_f32_e32 v83, v83
	v_rcp_f32_e32 v80, v80
	v_rcp_f32_e32 v81, v81
	v_pk_mul_f32 v[66:67], v[70:71], v[66:67]
	v_pk_mul_f32 v[64:65], v[68:69], v[64:65]
	v_pk_mul_f32 v[68:69], v[66:67], v[76:77]
	v_pk_mul_f32 v[66:67], v[64:65], v[78:79]
	v_pk_mul_f32 v[74:75], v[74:75], v[80:81]
	v_pk_mul_f32 v[72:73], v[72:73], v[82:83]
	v_pk_mul_f32 v[58:59], v[62:63], v[58:59]
	v_cvt_pk_bf16_f32 v64, v72, v73
	v_cvt_pk_bf16_f32 v65, v74, v75
	v_cvt_pk_bf16_f32 v66, v66, v67
	v_cvt_pk_bf16_f32 v67, v68, v69
	v_mad_u64_u32 v[68:69], s[52:53], v150, s54, v[112:113]
	v_mul_f32_e32 v70, 0xbfb8aa3b, v154
	v_mul_f32_e32 v71, v154, v154
	v_pk_mul_f32 v[74:75], v[62:63], v[70:71] op_sel_hi:[1,0]
	v_pk_mul_f32 v[76:77], v[60:61], v[70:71] op_sel_hi:[1,0]
	v_pk_mul_f32 v[56:57], v[60:61], v[56:57]
	v_pk_mul_f32 v[60:61], v[54:55], v[70:71] op_sel_hi:[1,0]
	v_pk_mul_f32 v[62:63], v[52:53], v[70:71] op_sel_hi:[1,0]
	v_rcp_f32_e32 v72, v71
	v_exp_f32_e32 v62, v62
	v_exp_f32_e32 v60, v60
	v_exp_f32_e32 v61, v61
	v_exp_f32_e32 v63, v63
	v_exp_f32_e32 v76, v76
	v_exp_f32_e32 v74, v74
	v_exp_f32_e32 v75, v75
	v_exp_f32_e32 v77, v77
	v_lshl_add_u64 v[68:69], v[68:69], 0, v[114:115]
	v_pk_fma_f32 v[60:61], v[60:61], v[72:73], v[72:73] op_sel_hi:[1,0,0]
	v_pk_fma_f32 v[62:63], v[62:63], v[72:73], v[72:73] op_sel_hi:[1,0,0]
	global_store_dwordx4 v[68:69], v[64:67], off
	v_rcp_f32_e32 v62, v62
	v_rcp_f32_e32 v60, v60
	v_pk_fma_f32 v[64:65], v[74:75], v[72:73], v[72:73] op_sel_hi:[1,0,0]
	v_pk_fma_f32 v[66:67], v[76:77], v[72:73], v[72:73] op_sel_hi:[1,0,0]
	v_rcp_f32_e32 v61, v61
	v_rcp_f32_e32 v63, v63
	v_rcp_f32_e32 v66, v66
	v_rcp_f32_e32 v67, v67
	v_rcp_f32_e32 v64, v64
	v_rcp_f32_e32 v65, v65
	v_pk_mul_f32 v[50:51], v[54:55], v[50:51]
	v_pk_mul_f32 v[48:49], v[52:53], v[48:49]
	v_pk_mul_f32 v[52:53], v[50:51], v[60:61]
	v_pk_mul_f32 v[50:51], v[48:49], v[62:63]
	v_pk_mul_f32 v[58:59], v[58:59], v[64:65]
	v_pk_mul_f32 v[56:57], v[56:57], v[66:67]
	v_pk_mul_f32 v[42:43], v[46:47], v[42:43]
	v_cvt_pk_bf16_f32 v48, v56, v57
	v_cvt_pk_bf16_f32 v49, v58, v59
	v_cvt_pk_bf16_f32 v50, v50, v51
	v_cvt_pk_bf16_f32 v51, v52, v53
	v_mad_u64_u32 v[52:53], s[52:53], v158, s54, v[112:113]
	v_mov_b32_e32 v54, v53
	v_mad_u64_u32 v[54:55], s[52:53], v159, s54, v[54:55]
	v_mov_b32_e32 v53, v54
	v_mul_f32_e32 v54, 0xbfb8aa3b, v155
	v_mul_f32_e32 v55, v155, v155
	v_pk_mul_f32 v[58:59], v[46:47], v[54:55] op_sel_hi:[1,0]
	v_pk_mul_f32 v[60:61], v[44:45], v[54:55] op_sel_hi:[1,0]
	v_pk_mul_f32 v[40:41], v[44:45], v[40:41]
	v_pk_mul_f32 v[44:45], v[38:39], v[54:55] op_sel_hi:[1,0]
	v_pk_mul_f32 v[46:47], v[36:37], v[54:55] op_sel_hi:[1,0]
	v_rcp_f32_e32 v56, v55
	v_exp_f32_e32 v46, v46
	v_exp_f32_e32 v44, v44
	v_exp_f32_e32 v45, v45
	v_exp_f32_e32 v47, v47
	v_exp_f32_e32 v60, v60
	v_exp_f32_e32 v58, v58
	v_exp_f32_e32 v59, v59
	v_exp_f32_e32 v61, v61
	v_lshl_add_u64 v[52:53], v[52:53], 0, v[114:115]
	v_pk_fma_f32 v[44:45], v[44:45], v[56:57], v[56:57] op_sel_hi:[1,0,0]
	v_pk_fma_f32 v[46:47], v[46:47], v[56:57], v[56:57] op_sel_hi:[1,0,0]
	global_store_dwordx4 v[52:53], v[48:51], off
	v_rcp_f32_e32 v46, v46
	v_rcp_f32_e32 v44, v44
	v_pk_fma_f32 v[48:49], v[58:59], v[56:57], v[56:57] op_sel_hi:[1,0,0]
	v_pk_fma_f32 v[50:51], v[60:61], v[56:57], v[56:57] op_sel_hi:[1,0,0]
	v_rcp_f32_e32 v45, v45
	v_rcp_f32_e32 v47, v47
	v_rcp_f32_e32 v50, v50
	v_rcp_f32_e32 v51, v51
	v_rcp_f32_e32 v48, v48
	v_rcp_f32_e32 v49, v49
	v_pk_mul_f32 v[34:35], v[38:39], v[34:35]
	v_pk_mul_f32 v[32:33], v[36:37], v[32:33]
	v_pk_mul_f32 v[36:37], v[34:35], v[44:45]
	v_pk_mul_f32 v[34:35], v[32:33], v[46:47]
	v_add_u32_e32 v38, 16, v146
	v_pk_mul_f32 v[42:43], v[42:43], v[48:49]
	v_pk_mul_f32 v[40:41], v[40:41], v[50:51]
	v_mul_f32_e32 v39, v148, v148
	v_cvt_pk_bf16_f32 v32, v40, v41
	v_cvt_pk_bf16_f32 v33, v42, v43
	v_cvt_pk_bf16_f32 v34, v34, v35
	v_cvt_pk_bf16_f32 v35, v36, v37
	v_mad_i64_i32 v[36:37], s[52:53], v38, s54, v[112:113]
	v_mul_f32_e32 v38, 0xbfb8aa3b, v148
	v_pk_mul_f32 v[42:43], v[30:31], v[38:39] op_sel_hi:[1,0]
	v_pk_mul_f32 v[44:45], v[28:29], v[38:39] op_sel_hi:[1,0]
	v_pk_mul_f32 v[26:27], v[30:31], v[26:27]
	v_pk_mul_f32 v[24:25], v[28:29], v[24:25]
	v_pk_mul_f32 v[28:29], v[22:23], v[38:39] op_sel_hi:[1,0]
	v_pk_mul_f32 v[30:31], v[20:21], v[38:39] op_sel_hi:[1,0]
	v_rcp_f32_e32 v40, v39
	v_exp_f32_e32 v30, v30
	v_exp_f32_e32 v28, v28
	v_exp_f32_e32 v29, v29
	v_exp_f32_e32 v31, v31
	v_exp_f32_e32 v44, v44
	v_exp_f32_e32 v42, v42
	v_exp_f32_e32 v43, v43
	v_exp_f32_e32 v45, v45
	v_lshl_add_u64 v[36:37], v[36:37], 0, v[114:115]
	v_pk_fma_f32 v[28:29], v[28:29], v[40:41], v[40:41] op_sel_hi:[1,0,0]
	v_pk_fma_f32 v[30:31], v[30:31], v[40:41], v[40:41] op_sel_hi:[1,0,0]
	global_store_dwordx4 v[36:37], v[32:35], off
	v_rcp_f32_e32 v30, v30
	v_rcp_f32_e32 v28, v28
	v_pk_fma_f32 v[32:33], v[42:43], v[40:41], v[40:41] op_sel_hi:[1,0,0]
	v_pk_fma_f32 v[34:35], v[44:45], v[40:41], v[40:41] op_sel_hi:[1,0,0]
	v_rcp_f32_e32 v29, v29
	v_rcp_f32_e32 v31, v31
	v_rcp_f32_e32 v34, v34
	v_rcp_f32_e32 v35, v35
	v_rcp_f32_e32 v32, v32
	v_rcp_f32_e32 v33, v33
	v_pk_mul_f32 v[18:19], v[22:23], v[18:19]
	v_pk_mul_f32 v[16:17], v[20:21], v[16:17]
	v_pk_mul_f32 v[20:21], v[18:19], v[28:29]
	v_pk_mul_f32 v[18:19], v[16:17], v[30:31]
	v_add_u32_e32 v22, 32, v146
	v_pk_mul_f32 v[26:27], v[26:27], v[32:33]
	v_pk_mul_f32 v[24:25], v[24:25], v[34:35]
	v_mul_f32_e32 v23, v149, v149
	v_cvt_pk_bf16_f32 v16, v24, v25
	v_cvt_pk_bf16_f32 v17, v26, v27
	v_cvt_pk_bf16_f32 v18, v18, v19
	v_cvt_pk_bf16_f32 v19, v20, v21
	v_mad_i64_i32 v[20:21], s[52:53], v22, s54, v[112:113]
	v_mul_f32_e32 v22, 0xbfb8aa3b, v149
	v_pk_mul_f32 v[26:27], v[14:15], v[22:23] op_sel_hi:[1,0]
	v_pk_mul_f32 v[28:29], v[12:13], v[22:23] op_sel_hi:[1,0]
	v_pk_mul_f32 v[10:11], v[14:15], v[10:11]
	v_pk_mul_f32 v[8:9], v[12:13], v[8:9]
	v_pk_mul_f32 v[12:13], v[6:7], v[22:23] op_sel_hi:[1,0]
	v_pk_mul_f32 v[14:15], v[4:5], v[22:23] op_sel_hi:[1,0]
	v_rcp_f32_e32 v24, v23
	v_exp_f32_e32 v14, v14
	v_exp_f32_e32 v12, v12
	v_exp_f32_e32 v13, v13
	v_exp_f32_e32 v15, v15
	v_exp_f32_e32 v28, v28
	v_exp_f32_e32 v26, v26
	v_exp_f32_e32 v27, v27
	v_exp_f32_e32 v29, v29
	v_lshl_add_u64 v[20:21], v[20:21], 0, v[114:115]
	v_pk_fma_f32 v[12:13], v[12:13], v[24:25], v[24:25] op_sel_hi:[1,0,0]
	v_pk_fma_f32 v[14:15], v[14:15], v[24:25], v[24:25] op_sel_hi:[1,0,0]
	global_store_dwordx4 v[20:21], v[16:19], off
	v_rcp_f32_e32 v14, v14
	v_rcp_f32_e32 v12, v12
	v_pk_fma_f32 v[16:17], v[26:27], v[24:25], v[24:25] op_sel_hi:[1,0,0]
	v_pk_fma_f32 v[18:19], v[28:29], v[24:25], v[24:25] op_sel_hi:[1,0,0]
	v_rcp_f32_e32 v13, v13
	v_rcp_f32_e32 v15, v15
	v_rcp_f32_e32 v18, v18
	v_rcp_f32_e32 v19, v19
	v_rcp_f32_e32 v16, v16
	v_rcp_f32_e32 v17, v17
	v_pk_mul_f32 v[2:3], v[6:7], v[2:3]
	v_pk_mul_f32 v[0:1], v[4:5], v[0:1]
	v_pk_mul_f32 v[4:5], v[2:3], v[12:13]
	v_pk_mul_f32 v[2:3], v[0:1], v[14:15]
	v_add_u32_e32 v6, 48, v146
	v_pk_mul_f32 v[10:11], v[10:11], v[16:17]
	v_pk_mul_f32 v[8:9], v[8:9], v[18:19]
	s_andn2_b64 vcc, exec, s[4:5]
	v_cvt_pk_bf16_f32 v0, v8, v9
	v_cvt_pk_bf16_f32 v1, v10, v11
	v_cvt_pk_bf16_f32 v2, v2, v3
	v_cvt_pk_bf16_f32 v3, v4, v5
	v_mad_i64_i32 v[4:5], s[52:53], v6, s54, v[112:113]
	v_lshl_add_u64 v[4:5], v[4:5], 0, v[114:115]
	s_mov_b64 s[4:5], -1
	global_store_dwordx4 v[4:5], v[0:3], off
	s_cbranch_vccnz .LBB0_2188
	s_andn2_b64 vcc, exec, s[8:9]
	s_cbranch_vccnz .LBB0_2187
	s_branch .LBB0_2187
.LBB0_2202:
	s_waitcnt vmcnt(0)
	s_and_b64 vcc, exec, s[42:43]
	s_cbranch_vccz .Lua_10
	s_barrier

.LBB0_2344:
	v_lshl_add_u32 v128, s41, 8, v194
	v_lshl_or_b32 v130, s42, 8, v196
	v_ashrrev_i32_e32 v131, 31, v130
	v_ashrrev_i32_e32 v129, 31, v128
	v_lshl_add_u64 v[132:133], v[130:131], 1, s[12:13]
	v_lshlrev_b64 v[134:135], 11, v[128:129]
	v_or_b32_e32 v228, 16, v128
	v_lshl_add_u64 v[134:135], v[132:133], 0, v[134:135]
	v_ashrrev_i32_e32 v229, 31, v228
	global_load_dwordx4 v[200:203], v[134:135], off
	global_load_dwordx4 v[204:207], v[134:135], off offset:256
	v_lshlrev_b64 v[134:135], 11, v[228:229]
	v_lshl_add_u64 v[134:135], v[132:133], 0, v[134:135]
	global_load_dwordx4 v[208:211], v[134:135], off
	v_or_b32_e32 v192, 32, v128
	v_ashrrev_i32_e32 v193, 31, v192
	global_load_dwordx4 v[212:215], v[134:135], off offset:256
	v_lshlrev_b64 v[182:183], 2, v[130:131]
	v_lshlrev_b64 v[130:131], 11, v[192:193]
	v_lshl_add_u64 v[130:131], v[132:133], 0, v[130:131]
	global_load_dwordx4 v[216:219], v[130:131], off
	v_or_b32_e32 v190, 48, v128
	v_add_u32_e32 v188, 0x80, v128
	v_add_u32_e32 v186, 0x90, v128
	v_add_u32_e32 v184, 0xa0, v128
	v_add_u32_e32 v180, 0xb0, v128
	v_ashrrev_i32_e32 v191, 31, v190
	v_ashrrev_i32_e32 v189, 31, v188
	v_ashrrev_i32_e32 v187, 31, v186
	v_ashrrev_i32_e32 v185, 31, v184
	v_ashrrev_i32_e32 v181, 31, v180
	v_lshlrev_b64 v[128:129], 12, v[128:129]
	v_lshlrev_b64 v[134:135], 11, v[190:191]
	v_lshlrev_b64 v[136:137], 11, v[188:189]
	v_lshlrev_b64 v[138:139], 11, v[186:187]
	v_lshlrev_b64 v[140:141], 11, v[184:185]
	v_lshlrev_b64 v[142:143], 11, v[180:181]
	v_lshl_add_u64 v[128:129], s[62:63], 0, v[128:129]
	v_lshl_add_u64 v[134:135], v[132:133], 0, v[134:135]
	v_lshl_add_u64 v[136:137], v[132:133], 0, v[136:137]
	v_lshl_add_u64 v[138:139], v[132:133], 0, v[138:139]
	v_lshl_add_u64 v[230:231], v[132:133], 0, v[140:141]
	v_lshl_add_u64 v[232:233], v[132:133], 0, v[142:143]
	v_lshl_add_u64 v[234:235], v[128:129], 0, v[182:183]
	global_load_dwordx4 v[220:223], v[130:131], off offset:256
	global_load_dwordx4 v[224:227], v[134:135], off
	global_load_dwordx4 v[160:163], v[134:135], off offset:256
	global_load_dwordx4 v[156:159], v[136:137], off
	global_load_dwordx4 v[152:155], v[136:137], off offset:256
	global_load_dwordx4 v[148:151], v[138:139], off
	global_load_dwordx4 v[144:147], v[138:139], off offset:256
	global_load_dwordx4 v[140:143], v[230:231], off
	s_nop 0
	global_load_dwordx4 v[136:139], v[230:231], off offset:256
	global_load_dwordx4 v[132:135], v[232:233], off
	global_load_dwordx4 v[128:131], v[232:233], off offset:256
	s_and_b64 vcc, exec, s[0:1]
	s_mov_b64 s[0:1], -1
	s_waitcnt vmcnt(0)
	v_lshlrev_b32_e32 v230, 16, v200
	v_and_b32_e32 v231, 0xffff0000, v200
	v_lshlrev_b32_e32 v200, 16, v201
	v_and_b32_e32 v201, 0xffff0000, v201
	v_lshlrev_b32_e32 v238, 16, v206
	v_and_b32_e32 v239, 0xffff0000, v206
	v_lshlrev_b32_e32 v232, 16, v202
	v_and_b32_e32 v233, 0xffff0000, v202
	v_lshlrev_b32_e32 v202, 16, v203
	v_and_b32_e32 v203, 0xffff0000, v203
	v_lshlrev_b32_e32 v236, 16, v204
	v_and_b32_e32 v237, 0xffff0000, v204
	v_lshlrev_b32_e32 v204, 16, v205
	v_and_b32_e32 v205, 0xffff0000, v205
	v_lshlrev_b32_e32 v206, 16, v207
	v_and_b32_e32 v207, 0xffff0000, v207
	v_pk_fma_f32 v[126:127], v[126:127], 0.5, v[200:201] op_sel_hi:[1,0,1]
	v_pk_fma_f32 v[124:125], v[124:125], 0.5, v[230:231] op_sel_hi:[1,0,1]
	v_pk_fma_f32 v[112:113], v[112:113], 0.5, v[238:239] op_sel_hi:[1,0,1]
	v_pk_fma_f32 v[122:123], v[122:123], 0.5, v[202:203] op_sel_hi:[1,0,1]
	v_pk_fma_f32 v[120:121], v[120:121], 0.5, v[232:233] op_sel_hi:[1,0,1]
	v_pk_fma_f32 v[118:119], v[118:119], 0.5, v[204:205] op_sel_hi:[1,0,1]
	v_pk_fma_f32 v[116:117], v[116:117], 0.5, v[236:237] op_sel_hi:[1,0,1]
	v_pk_fma_f32 v[114:115], v[114:115], 0.5, v[206:207] op_sel_hi:[1,0,1]
	global_store_dwordx4 v[234:235], v[124:127], off nt
	global_store_dwordx4 v[234:235], v[120:123], off offset:16 nt
	global_store_dwordx4 v[234:235], v[116:119], off offset:512 nt
	global_store_dwordx4 v[234:235], v[112:115], off offset:528 nt
	v_lshlrev_b32_e32 v200, 16, v208
	v_and_b32_e32 v201, 0xffff0000, v208
	v_lshlrev_b32_e32 v112, 16, v210
	v_and_b32_e32 v113, 0xffff0000, v210
	v_pk_fma_f32 v[104:105], v[104:105], 0.5, v[112:113] op_sel_hi:[1,0,1]
	v_lshlrev_b64 v[112:113], 12, v[228:229]
	v_lshlrev_b32_e32 v202, 16, v209
	v_and_b32_e32 v203, 0xffff0000, v209
	v_lshlrev_b32_e32 v114, 16, v211
	v_and_b32_e32 v115, 0xffff0000, v211
	v_lshl_add_u64 v[112:113], s[62:63], 0, v[112:113]
	v_pk_fma_f32 v[110:111], v[110:111], 0.5, v[202:203] op_sel_hi:[1,0,1]
	v_pk_fma_f32 v[108:109], v[108:109], 0.5, v[200:201] op_sel_hi:[1,0,1]
	v_pk_fma_f32 v[106:107], v[106:107], 0.5, v[114:115] op_sel_hi:[1,0,1]
	v_lshl_add_u64 v[112:113], v[112:113], 0, v[182:183]
	global_store_dwordx4 v[112:113], v[108:111], off nt
	global_store_dwordx4 v[112:113], v[104:107], off offset:16 nt
	s_nop 0
	v_lshlrev_b32_e32 v108, 16, v214
	v_lshlrev_b32_e32 v104, 16, v212
	v_and_b32_e32 v105, 0xffff0000, v212
	v_lshlrev_b32_e32 v106, 16, v213
	v_and_b32_e32 v107, 0xffff0000, v213
	v_and_b32_e32 v109, 0xffff0000, v214
	v_lshlrev_b32_e32 v110, 16, v215
	v_and_b32_e32 v111, 0xffff0000, v215
	v_pk_fma_f32 v[102:103], v[102:103], 0.5, v[106:107] op_sel_hi:[1,0,1]
	v_pk_fma_f32 v[100:101], v[100:101], 0.5, v[104:105] op_sel_hi:[1,0,1]
	v_pk_fma_f32 v[92:93], v[92:93], 0.5, v[108:109] op_sel_hi:[1,0,1]
	v_pk_fma_f32 v[94:95], v[94:95], 0.5, v[110:111] op_sel_hi:[1,0,1]
	global_store_dwordx4 v[112:113], v[100:103], off offset:512 nt
	global_store_dwordx4 v[112:113], v[92:95], off offset:528 nt
	s_nop 0
	v_lshlrev_b32_e32 v100, 16, v218
	v_lshlrev_b32_e32 v92, 16, v216
	v_and_b32_e32 v93, 0xffff0000, v216
	v_pk_fma_f32 v[92:93], v[96:97], 0.5, v[92:93] op_sel_hi:[1,0,1]
	v_lshlrev_b64 v[96:97], 12, v[192:193]
	v_lshlrev_b32_e32 v94, 16, v217
	v_and_b32_e32 v95, 0xffff0000, v217
	v_and_b32_e32 v101, 0xffff0000, v218
	v_lshlrev_b32_e32 v102, 16, v219
	v_and_b32_e32 v103, 0xffff0000, v219
	v_lshl_add_u64 v[96:97], s[62:63], 0, v[96:97]
	v_pk_fma_f32 v[94:95], v[98:99], 0.5, v[94:95] op_sel_hi:[1,0,1]
	v_pk_fma_f32 v[90:91], v[90:91], 0.5, v[102:103] op_sel_hi:[1,0,1]
	v_pk_fma_f32 v[88:89], v[88:89], 0.5, v[100:101] op_sel_hi:[1,0,1]
	v_lshl_add_u64 v[96:97], v[96:97], 0, v[182:183]
	global_store_dwordx4 v[96:97], v[92:95], off nt
	global_store_dwordx4 v[96:97], v[88:91], off offset:16 nt
	s_nop 0
	v_lshlrev_b32_e32 v92, 16, v222
	v_lshlrev_b32_e32 v88, 16, v220
	v_and_b32_e32 v89, 0xffff0000, v220
	v_lshlrev_b32_e32 v90, 16, v221
	v_and_b32_e32 v91, 0xffff0000, v221
	v_and_b32_e32 v93, 0xffff0000, v222
	v_lshlrev_b32_e32 v94, 16, v223
	v_and_b32_e32 v95, 0xffff0000, v223
	v_pk_fma_f32 v[86:87], v[86:87], 0.5, v[90:91] op_sel_hi:[1,0,1]
	v_pk_fma_f32 v[84:85], v[84:85], 0.5, v[88:89] op_sel_hi:[1,0,1]
	v_pk_fma_f32 v[76:77], v[76:77], 0.5, v[92:93] op_sel_hi:[1,0,1]
	v_pk_fma_f32 v[78:79], v[78:79], 0.5, v[94:95] op_sel_hi:[1,0,1]
	global_store_dwordx4 v[96:97], v[84:87], off offset:512 nt
	global_store_dwordx4 v[96:97], v[76:79], off offset:528 nt
	s_nop 0
	v_lshlrev_b32_e32 v84, 16, v226
	v_lshlrev_b32_e32 v76, 16, v224
	v_and_b32_e32 v77, 0xffff0000, v224
	v_pk_fma_f32 v[76:77], v[80:81], 0.5, v[76:77] op_sel_hi:[1,0,1]
	v_lshlrev_b64 v[80:81], 12, v[190:191]
	v_lshlrev_b32_e32 v78, 16, v225
	v_and_b32_e32 v79, 0xffff0000, v225
	v_and_b32_e32 v85, 0xffff0000, v226
	v_lshlrev_b32_e32 v86, 16, v227
	v_and_b32_e32 v87, 0xffff0000, v227
	v_lshl_add_u64 v[80:81], s[62:63], 0, v[80:81]
	v_pk_fma_f32 v[78:79], v[82:83], 0.5, v[78:79] op_sel_hi:[1,0,1]
	v_pk_fma_f32 v[74:75], v[74:75], 0.5, v[86:87] op_sel_hi:[1,0,1]
	v_pk_fma_f32 v[72:73], v[72:73], 0.5, v[84:85] op_sel_hi:[1,0,1]
	v_lshl_add_u64 v[80:81], v[80:81], 0, v[182:183]
	global_store_dwordx4 v[80:81], v[76:79], off nt
	global_store_dwordx4 v[80:81], v[72:75], off offset:16 nt
	s_nop 0
	v_lshlrev_b32_e32 v76, 16, v162
	v_lshlrev_b32_e32 v72, 16, v160
	v_and_b32_e32 v73, 0xffff0000, v160
	v_lshlrev_b32_e32 v74, 16, v161
	v_and_b32_e32 v75, 0xffff0000, v161
	v_and_b32_e32 v77, 0xffff0000, v162
	v_lshlrev_b32_e32 v78, 16, v163
	v_and_b32_e32 v79, 0xffff0000, v163
	v_pk_fma_f32 v[70:71], v[70:71], 0.5, v[74:75] op_sel_hi:[1,0,1]
	v_pk_fma_f32 v[68:69], v[68:69], 0.5, v[72:73] op_sel_hi:[1,0,1]
	v_pk_fma_f32 v[64:65], v[64:65], 0.5, v[76:77] op_sel_hi:[1,0,1]
	v_pk_fma_f32 v[66:67], v[66:67], 0.5, v[78:79] op_sel_hi:[1,0,1]
	global_store_dwordx4 v[80:81], v[68:71], off offset:512 nt
	global_store_dwordx4 v[80:81], v[64:67], off offset:528 nt
	s_nop 0
	v_lshlrev_b32_e32 v68, 16, v158
	v_lshlrev_b32_e32 v64, 16, v156
	v_and_b32_e32 v65, 0xffff0000, v156
	v_pk_fma_f32 v[60:61], v[60:61], 0.5, v[64:65] op_sel_hi:[1,0,1]
	v_lshlrev_b64 v[64:65], 12, v[188:189]
	v_lshlrev_b32_e32 v66, 16, v157
	v_and_b32_e32 v67, 0xffff0000, v157
	v_and_b32_e32 v69, 0xffff0000, v158
	v_lshlrev_b32_e32 v70, 16, v159
	v_and_b32_e32 v71, 0xffff0000, v159
	v_lshl_add_u64 v[64:65], s[62:63], 0, v[64:65]
	v_pk_fma_f32 v[62:63], v[62:63], 0.5, v[66:67] op_sel_hi:[1,0,1]
	v_pk_fma_f32 v[58:59], v[58:59], 0.5, v[70:71] op_sel_hi:[1,0,1]
	v_pk_fma_f32 v[56:57], v[56:57], 0.5, v[68:69] op_sel_hi:[1,0,1]
	v_lshl_add_u64 v[64:65], v[64:65], 0, v[182:183]
	global_store_dwordx4 v[64:65], v[60:63], off nt
	global_store_dwordx4 v[64:65], v[56:59], off offset:16 nt
	s_nop 0
	v_lshlrev_b32_e32 v60, 16, v154
	v_lshlrev_b32_e32 v56, 16, v152
	v_and_b32_e32 v57, 0xffff0000, v152
	v_lshlrev_b32_e32 v58, 16, v153
	v_and_b32_e32 v59, 0xffff0000, v153
	v_and_b32_e32 v61, 0xffff0000, v154
	v_lshlrev_b32_e32 v62, 16, v155
	v_and_b32_e32 v63, 0xffff0000, v155
	v_pk_fma_f32 v[54:55], v[54:55], 0.5, v[58:59] op_sel_hi:[1,0,1]
	v_pk_fma_f32 v[52:53], v[52:53], 0.5, v[56:57] op_sel_hi:[1,0,1]
	v_pk_fma_f32 v[44:45], v[44:45], 0.5, v[60:61] op_sel_hi:[1,0,1]
	v_pk_fma_f32 v[46:47], v[46:47], 0.5, v[62:63] op_sel_hi:[1,0,1]
	global_store_dwordx4 v[64:65], v[52:55], off offset:512 nt
	global_store_dwordx4 v[64:65], v[44:47], off offset:528 nt
	s_nop 0
	v_lshlrev_b32_e32 v52, 16, v150
	v_lshlrev_b32_e32 v44, 16, v148
	v_and_b32_e32 v45, 0xffff0000, v148
	v_pk_fma_f32 v[44:45], v[48:49], 0.5, v[44:45] op_sel_hi:[1,0,1]
	v_lshlrev_b64 v[48:49], 12, v[186:187]
	v_lshlrev_b32_e32 v46, 16, v149
	v_and_b32_e32 v47, 0xffff0000, v149
	v_and_b32_e32 v53, 0xffff0000, v150
	v_lshlrev_b32_e32 v54, 16, v151
	v_and_b32_e32 v55, 0xffff0000, v151
	v_lshl_add_u64 v[48:49], s[62:63], 0, v[48:49]
	v_pk_fma_f32 v[46:47], v[50:51], 0.5, v[46:47] op_sel_hi:[1,0,1]
	v_pk_fma_f32 v[42:43], v[42:43], 0.5, v[54:55] op_sel_hi:[1,0,1]
	v_pk_fma_f32 v[40:41], v[40:41], 0.5, v[52:53] op_sel_hi:[1,0,1]
	v_lshl_add_u64 v[48:49], v[48:49], 0, v[182:183]
	global_store_dwordx4 v[48:49], v[44:47], off nt
	global_store_dwordx4 v[48:49], v[40:43], off offset:16 nt
	s_nop 0
	v_lshlrev_b32_e32 v44, 16, v146
	v_lshlrev_b32_e32 v40, 16, v144
	v_and_b32_e32 v41, 0xffff0000, v144
	v_lshlrev_b32_e32 v42, 16, v145
	v_and_b32_e32 v43, 0xffff0000, v145
	v_and_b32_e32 v45, 0xffff0000, v146
	v_lshlrev_b32_e32 v46, 16, v147
	v_and_b32_e32 v47, 0xffff0000, v147
	v_pk_fma_f32 v[38:39], v[38:39], 0.5, v[42:43] op_sel_hi:[1,0,1]
	v_pk_fma_f32 v[36:37], v[36:37], 0.5, v[40:41] op_sel_hi:[1,0,1]
	v_pk_fma_f32 v[28:29], v[28:29], 0.5, v[44:45] op_sel_hi:[1,0,1]
	v_pk_fma_f32 v[30:31], v[30:31], 0.5, v[46:47] op_sel_hi:[1,0,1]
	global_store_dwordx4 v[48:49], v[36:39], off offset:512 nt
	global_store_dwordx4 v[48:49], v[28:31], off offset:528 nt
	s_nop 0
	v_lshlrev_b32_e32 v36, 16, v142
	v_lshlrev_b32_e32 v28, 16, v140
	v_and_b32_e32 v29, 0xffff0000, v140
	v_pk_fma_f32 v[28:29], v[32:33], 0.5, v[28:29] op_sel_hi:[1,0,1]
	v_lshlrev_b64 v[32:33], 12, v[184:185]
	v_lshlrev_b32_e32 v30, 16, v141
	v_and_b32_e32 v31, 0xffff0000, v141
	v_and_b32_e32 v37, 0xffff0000, v142
	v_lshlrev_b32_e32 v38, 16, v143
	v_and_b32_e32 v39, 0xffff0000, v143
	v_lshl_add_u64 v[32:33], s[62:63], 0, v[32:33]
	v_pk_fma_f32 v[30:31], v[34:35], 0.5, v[30:31] op_sel_hi:[1,0,1]
	v_pk_fma_f32 v[26:27], v[26:27], 0.5, v[38:39] op_sel_hi:[1,0,1]
	v_pk_fma_f32 v[24:25], v[24:25], 0.5, v[36:37] op_sel_hi:[1,0,1]
	v_lshl_add_u64 v[32:33], v[32:33], 0, v[182:183]
	global_store_dwordx4 v[32:33], v[28:31], off nt
	global_store_dwordx4 v[32:33], v[24:27], off offset:16 nt
	s_nop 0
	v_lshlrev_b32_e32 v28, 16, v138
	v_lshlrev_b32_e32 v24, 16, v136
	v_and_b32_e32 v25, 0xffff0000, v136
	v_lshlrev_b32_e32 v26, 16, v137
	v_and_b32_e32 v27, 0xffff0000, v137
	v_and_b32_e32 v29, 0xffff0000, v138
	v_lshlrev_b32_e32 v30, 16, v139
	v_and_b32_e32 v31, 0xffff0000, v139
	v_pk_fma_f32 v[22:23], v[22:23], 0.5, v[26:27] op_sel_hi:[1,0,1]
	v_pk_fma_f32 v[20:21], v[20:21], 0.5, v[24:25] op_sel_hi:[1,0,1]
	v_pk_fma_f32 v[12:13], v[12:13], 0.5, v[28:29] op_sel_hi:[1,0,1]
	v_pk_fma_f32 v[14:15], v[14:15], 0.5, v[30:31] op_sel_hi:[1,0,1]
	global_store_dwordx4 v[32:33], v[20:23], off offset:512 nt
	global_store_dwordx4 v[32:33], v[12:15], off offset:528 nt
	s_nop 0
	v_lshlrev_b32_e32 v20, 16, v134
	v_lshlrev_b32_e32 v12, 16, v132
	v_and_b32_e32 v13, 0xffff0000, v132
	v_pk_fma_f32 v[12:13], v[16:17], 0.5, v[12:13] op_sel_hi:[1,0,1]
	v_lshlrev_b64 v[16:17], 12, v[180:181]
	v_lshlrev_b32_e32 v14, 16, v133
	v_and_b32_e32 v15, 0xffff0000, v133
	v_and_b32_e32 v21, 0xffff0000, v134
	v_lshlrev_b32_e32 v22, 16, v135
	v_and_b32_e32 v23, 0xffff0000, v135
	v_lshl_add_u64 v[16:17], s[62:63], 0, v[16:17]
	v_pk_fma_f32 v[14:15], v[18:19], 0.5, v[14:15] op_sel_hi:[1,0,1]
	v_pk_fma_f32 v[10:11], v[10:11], 0.5, v[22:23] op_sel_hi:[1,0,1]
	v_pk_fma_f32 v[8:9], v[8:9], 0.5, v[20:21] op_sel_hi:[1,0,1]
	v_lshl_add_u64 v[16:17], v[16:17], 0, v[182:183]
	global_store_dwordx4 v[16:17], v[12:15], off nt
	global_store_dwordx4 v[16:17], v[8:11], off offset:16 nt
	s_nop 0
	v_lshlrev_b32_e32 v12, 16, v130
	v_lshlrev_b32_e32 v8, 16, v128
	v_and_b32_e32 v9, 0xffff0000, v128
	v_lshlrev_b32_e32 v10, 16, v129
	v_and_b32_e32 v11, 0xffff0000, v129
	v_and_b32_e32 v13, 0xffff0000, v130
	v_lshlrev_b32_e32 v14, 16, v131
	v_and_b32_e32 v15, 0xffff0000, v131
	v_pk_fma_f32 v[6:7], v[6:7], 0.5, v[10:11] op_sel_hi:[1,0,1]
	v_pk_fma_f32 v[4:5], v[4:5], 0.5, v[8:9] op_sel_hi:[1,0,1]
	v_pk_fma_f32 v[2:3], v[2:3], 0.5, v[14:15] op_sel_hi:[1,0,1]
	v_pk_fma_f32 v[0:1], v[0:1], 0.5, v[12:13] op_sel_hi:[1,0,1]
	global_store_dwordx4 v[16:17], v[4:7], off offset:512 nt
	global_store_dwordx4 v[16:17], v[0:3], off offset:528 nt
	s_cbranch_vccnz .LBB0_2329
	s_andn2_b64 vcc, exec, s[6:7]
	s_cbranch_vccnz .LBB0_2328
	s_branch .LBB0_2328
.LBB0_2347:
	s_waitcnt vmcnt(0)
	s_and_b64 vcc, exec, s[10:11]
	s_cbranch_vccz .Lua_11
	s_barrier
